# rotation-free MFMA groups in snake order with alternating k so consecutive MFMAs share the accumulator or one operand fragment (f32 accumulation order of the two k-steps may swap)
# speedup vs baseline: 1.0068x; 1.0068x over previous
;     __host__ __device__ __forceinline__ bool next(int i, Unit& u) const { const int vv = vid + (i / 5) * G; if (vv >= 256) return false; u.pm = vv >> 2; u.pn = (vv & 3) + 4 * (i % 5); return true; }
; #define PG8_STAGE(bufoff, gbase, voff) do { _Pragma("unroll") for (int _i = 0; _i < 2; ++_i) \
;         __builtin_amdgcn_global_load_lds((const unsigned*)((const char*)(gbase) + (voff)[_i]), (PG8_LAS unsigned*)(lds + (bufoff) + ldsw + _i * 8192), 16, 0, 0); } while (0)
; #define PG8_LDA(dst, b, h) do { _Pragma("unroll") for (int m = 0; m < 4; ++m) _Pragma("unroll") for (int k = 0; k < 2; ++k) dst[m][k] = *(const PG8_LAS bf16x8*)(lds + PG8_SA(b, h) + aoff + m * 2048 + k * 1024); } while (0)
; #define PG8_LDB(dst, b, h) do { _Pragma("unroll") for (int n = 0; n < 2; ++n) _Pragma("unroll") for (int k = 0; k < 2; ++k) dst[n][k] = *(const PG8_LAS bf16x8*)(lds + PG8_SB(b, h) + boff + n * 2048 + k * 1024); } while (0)
; #define PG8_WAIT_V(n) asm volatile("s_waitcnt vmcnt(" #n ")" ::: "memory")
; #define PG8_WAIT_L(n) asm volatile("s_waitcnt lgkmcnt(" #n ")" ::: "memory")
; #define PG8_BAR __builtin_amdgcn_s_barrier()
; #define PG8_SCHED __builtin_amdgcn_sched_barrier(0)
;     ...
;         const bool has_next = S.next(ui + 1, nxt);
;         const char* nA = has_next ? (const char*)g.A + (size_t)nxt.pm * tstepA + (size_t)nxt.pn * APN + kofA : cA; const char* nB = has_next ? (const char*)g.Bt + (size_t)nxt.pn * tstepB + S.b_off(nxt) + kofB : cB;
;         for (int t = 0; t < nt; t += 2) {
;             const bool last = (t == nt - 2);
;             const char* a1 = cA + (ptrdiff_t)(t + 1) * kstepA;
;             const char* a2 = last ? nA : cA + (ptrdiff_t)(t + 2) * kstepA; const char* b2 = last ? nB : cB + (ptrdiff_t)(t + 2) * kstep;
;             const char* a3 = a2 + kstepA; const char* b3 = b2 + kstep;
;             if (last && has_next) S.a_ready(nxt);
;             if constexpr (SP2) {
;             PG8_LDB(B0, 0, 0); PG8_LDB(B1, 0, 1); PG8_SCHED; PG8_LDA(At, 0, 0); PG8_STAGE(PG8_SA(1, 1), a1 + hstepA, voffA);
;             PG8_WAIT_V(8); PG8_WAIT_L(0); PG8_BAR; PG8_MMA(0, 0, At, B0); PG8_MMA(0, 1, At, B1); PG8_BAR; PG8_SCHED;
;             PG8_LDA(At, 0, 1); PG8_STAGE(PG8_SB(0, 0), b2, voffB); PG8_STAGE(PG8_SB(0, 1), b2 + hstepB, voffB); PG8_STAGE(PG8_SA(0, 0), a2, voffA);
.LBB0_97:
	s_mov_b64 s[30:31], s[6:7]
	s_ashr_i32 s6, s14, 2
	s_and_b32 s6, s6, -8
	s_and_b32 s7, s14, 7
	s_mov_b32 s20, s58
	s_mov_b32 s21, s57
	v_cmp_lt_i64_e64 s[4:5], s[14:15], v[138:139]
	s_bfe_u32 s57, s14, 0x20003
	s_or_b32 s58, s6, s7
	s_and_b64 s[6:7], s[4:5], exec
	s_cselect_b32 s24, s58, s20
	s_cselect_b32 s6, s57, s21
	s_ashr_i32 s25, s24, 31
	s_lshl_b64 s[20:21], s[24:25], 20
	s_add_u32 s20, s2, s20
	s_addc_u32 s21, s3, s21
	s_ashr_i32 s7, s6, 31
	s_lshl_b64 s[6:7], s[6:7], 17
	s_add_u32 s20, s20, s6
	s_addc_u32 s21, s21, s7
	s_and_b64 s[28:29], s[4:5], exec
	ds_read_b128 v[0:3], v141
	ds_read_b128 v[4:7], v141 offset:1024
	ds_read_b128 v[8:11], v141 offset:2048
	ds_read_b128 v[12:15], v141 offset:3072
	ds_read_b128 v[16:19], v142
	ds_read_b128 v[20:23], v142 offset:1024
	ds_read_b128 v[24:27], v142 offset:2048
	ds_read_b128 v[28:31], v142 offset:3072
	s_cselect_b32 s29, s21, s27
	s_cselect_b32 s28, s20, s26
	s_add_u32 s25, s33, s6
	s_addc_u32 s34, s36, s7
	s_ashr_i32 s6, s24, 3
	s_ashr_i32 s7, s6, 31
	s_lshl_b64 s[6:7], s[6:7], 19
	s_add_u32 s6, s25, s6
	s_addc_u32 s7, s34, s7
	s_and_b64 s[24:25], s[4:5], exec
	s_cselect_b32 s25, s7, s31
	s_cselect_b32 s24, s6, s30
	s_add_u32 s60, s26, 0x10000
	s_addc_u32 s61, s27, 0
	s_add_u32 s34, s26, 0x18000
	s_addc_u32 s35, s27, 0
	s_add_u32 s62, s26, 0xc000
	s_addc_u32 s63, s27, 0
	s_mov_b32 m0, s46
	ds_read_b128 v[32:35], v143
	ds_read_b128 v[36:39], v143 offset:1024
	ds_read_b128 v[40:43], v143 offset:2048
	ds_read_b128 v[44:47], v143 offset:3072
	ds_read_b128 v[48:51], v143 offset:4096
	ds_read_b128 v[52:55], v143 offset:5120
	ds_read_b128 v[56:59], v143 offset:6144
	ds_read_b128 v[60:63], v143 offset:7168
	global_load_lds_dwordx4 v134, s[62:63]
	v_lshl_add_u64 v[64:65], s[62:63], 0, v[130:131]
	s_mov_b32 m0, s47
	s_nop 0
	global_load_lds_dwordx4 v[64:65], off
	s_waitcnt vmcnt(8)
	s_waitcnt lgkmcnt(0)
	s_barrier
	s_setprio 1
	s_waitcnt lgkmcnt(0)
	v_mfma_f32_16x16x32_bf16 v[64:67], v[0:3], v[32:35], 0
	v_mfma_f32_16x16x32_bf16 v[64:67], v[4:7], v[36:39], v[64:67]
	v_mfma_f32_16x16x32_bf16 v[68:71], v[8:11], v[32:35], 0
	v_mfma_f32_16x16x32_bf16 v[68:71], v[12:15], v[36:39], v[68:71]
	v_mfma_f32_16x16x32_bf16 v[72:75], v[0:3], v[40:43], 0
	v_mfma_f32_16x16x32_bf16 v[72:75], v[4:7], v[44:47], v[72:75]
	v_mfma_f32_16x16x32_bf16 v[76:79], v[8:11], v[40:43], 0
	v_mfma_f32_16x16x32_bf16 v[76:79], v[12:15], v[44:47], v[76:79]
	v_mfma_f32_16x16x32_bf16 v[80:83], v[0:3], v[48:51], 0
	v_mfma_f32_16x16x32_bf16 v[80:83], v[4:7], v[52:55], v[80:83]
	v_mfma_f32_16x16x32_bf16 v[84:87], v[8:11], v[48:51], 0
	v_mfma_f32_16x16x32_bf16 v[84:87], v[12:15], v[52:55], v[84:87]
	v_mfma_f32_16x16x32_bf16 v[88:91], v[0:3], v[56:59], 0
	v_mfma_f32_16x16x32_bf16 v[88:91], v[4:7], v[60:63], v[88:91]
	v_mfma_f32_16x16x32_bf16 v[92:95], v[8:11], v[56:59], 0
	v_mfma_f32_16x16x32_bf16 v[92:95], v[12:15], v[60:63], v[92:95]
	s_setprio 0
	s_setprio 1
	v_mfma_f32_16x16x32_bf16 v[96:99], v[16:19], v[32:35], 0
	v_mfma_f32_16x16x32_bf16 v[96:99], v[20:23], v[36:39], v[96:99]
	v_mfma_f32_16x16x32_bf16 v[32:35], v[24:27], v[32:35], 0
	v_mfma_f32_16x16x32_bf16 v[32:35], v[28:31], v[36:39], v[32:35]
	v_mfma_f32_16x16x32_bf16 v[36:39], v[16:19], v[40:43], 0
	v_mfma_f32_16x16x32_bf16 v[36:39], v[20:23], v[44:47], v[36:39]
	v_mfma_f32_16x16x32_bf16 v[40:43], v[24:27], v[40:43], 0
	v_mfma_f32_16x16x32_bf16 v[40:43], v[28:31], v[44:47], v[40:43]
	v_mfma_f32_16x16x32_bf16 v[44:47], v[16:19], v[48:51], 0
	v_mfma_f32_16x16x32_bf16 v[44:47], v[20:23], v[52:55], v[44:47]
	v_mfma_f32_16x16x32_bf16 v[48:51], v[24:27], v[48:51], 0
	v_mfma_f32_16x16x32_bf16 v[48:51], v[28:31], v[52:55], v[48:51]
	v_mfma_f32_16x16x32_bf16 v[52:55], v[16:19], v[56:59], 0
	v_mfma_f32_16x16x32_bf16 v[52:55], v[20:23], v[60:63], v[52:55]
	v_mfma_f32_16x16x32_bf16 v[56:59], v[24:27], v[56:59], 0
	v_mfma_f32_16x16x32_bf16 v[56:59], v[28:31], v[60:63], v[56:59]
	s_setprio 0
	s_barrier
	v_lshl_add_u64 v[210:211], s[30:31], 0, v[132:133]
	s_mov_b32 m0, s48
	v_lshl_add_u64 v[146:147], v[210:211], 0, s[16:17]
	v_lshl_add_u64 v[212:213], s[30:31], 0, v[128:129]
	s_add_u32 s62, s30, 0x10100
	ds_read_b128 v[60:63], v143 offset:16384
	ds_read_b128 v[100:103], v143 offset:17408
	ds_read_b128 v[104:107], v143 offset:18432
	ds_read_b128 v[108:111], v143 offset:19456
	ds_read_b128 v[112:115], v143 offset:20480
	ds_read_b128 v[116:119], v143 offset:21504
	ds_read_b128 v[120:123], v143 offset:22528
	ds_read_b128 v[124:127], v143 offset:23552
	global_load_lds_dwordx4 v[146:147], off
	v_lshl_add_u64 v[146:147], v[212:213], 0, s[16:17]
	s_mov_b32 m0, s50
	s_addc_u32 s63, s31, 0
	global_load_lds_dwordx4 v[146:147], off
	s_mov_b32 m0, s51
	s_nop 0
	global_load_lds_dwordx4 v132, s[62:63]
	s_mov_b32 m0, s52
	s_nop 0
	global_load_lds_dwordx4 v128, s[62:63]
	s_mov_b32 m0, s23
	s_nop 0
	global_load_lds_dwordx4 v134, s[60:61]
	v_lshl_add_u64 v[146:147], s[60:61], 0, v[130:131]
	s_mov_b32 m0, s37
	s_nop 0
	global_load_lds_dwordx4 v[146:147], off
	s_waitcnt vmcnt(8)
	s_waitcnt lgkmcnt(0)
	s_barrier
; #define PG8_STAGE(bufoff, gbase, voff) do { _Pragma("unroll") for (int _i = 0; _i < 2; ++_i) \
;         __builtin_amdgcn_global_load_lds((const unsigned*)((const char*)(gbase) + (voff)[_i]), (PG8_LAS unsigned*)(lds + (bufoff) + ldsw + _i * 8192), 16, 0, 0); } while (0)
; #define PG8_LDA(dst, b, h) do { _Pragma("unroll") for (int m = 0; m < 4; ++m) _Pragma("unroll") for (int k = 0; k < 2; ++k) dst[m][k] = *(const PG8_LAS bf16x8*)(lds + PG8_SA(b, h) + aoff + m * 2048 + k * 1024); } while (0)
; #define PG8_LDB(dst, b, h) do { _Pragma("unroll") for (int n = 0; n < 2; ++n) _Pragma("unroll") for (int k = 0; k < 2; ++k) dst[n][k] = *(const PG8_LAS bf16x8*)(lds + PG8_SB(b, h) + boff + n * 2048 + k * 1024); } while (0)
; #define PG8_MMA(ai, bj, At, Bt) do { __builtin_amdgcn_s_setprio(1); _Pragma("unroll") for (int m = 0; m < 4; ++m) _Pragma("unroll") for (int n = 0; n < 2; ++n) _Pragma("unroll") for (int k = 0; k < 2; ++k) \
;         acc[ai][bj][m][n] = __builtin_amdgcn_mfma_f32_16x16x32_bf16(Bt[n][k], At[m][k], acc[ai][bj][m][n], 0, 0, 0); __builtin_amdgcn_s_setprio(0); } while (0)
; #define PG8_WAIT_V(n) asm volatile("s_waitcnt vmcnt(" #n ")" ::: "memory")
; #define PG8_WAIT_L(n) asm volatile("s_waitcnt lgkmcnt(" #n ")" ::: "memory")
; #define PG8_BAR __builtin_amdgcn_s_barrier()
; #define PG8_SCHED __builtin_amdgcn_sched_barrier(0)
;     ...
;             PG8_WAIT_V(8); PG8_WAIT_L(0); PG8_BAR; PG8_MMA(1, 0, At, B0); PG8_MMA(1, 1, At, B1); PG8_BAR; PG8_SCHED;
;             PG8_LDB(B0, 1, 0); PG8_LDB(B1, 1, 1); PG8_SCHED; PG8_LDA(At, 1, 0); PG8_STAGE(PG8_SA(0, 1), a2 + hstepA, voffA);
;             PG8_WAIT_V(8); PG8_WAIT_L(0); PG8_BAR; PG8_MMA(0, 0, At, B0); PG8_MMA(0, 1, At, B1); PG8_BAR; PG8_SCHED;
	s_setprio 1
	s_waitcnt lgkmcnt(0)
	v_mfma_f32_16x16x32_bf16 v[146:149], v[0:3], v[60:63], 0
	v_mfma_f32_16x16x32_bf16 v[146:149], v[4:7], v[100:103], v[146:149]
	v_mfma_f32_16x16x32_bf16 v[154:157], v[0:3], v[104:107], 0
	v_mfma_f32_16x16x32_bf16 v[154:157], v[4:7], v[108:111], v[154:157]
	v_mfma_f32_16x16x32_bf16 v[162:165], v[0:3], v[112:115], 0
	v_mfma_f32_16x16x32_bf16 v[162:165], v[4:7], v[116:119], v[162:165]
	v_mfma_f32_16x16x32_bf16 v[0:3], v[0:3], v[120:123], 0
	v_mfma_f32_16x16x32_bf16 v[0:3], v[4:7], v[124:127], v[0:3]
	v_mfma_f32_16x16x32_bf16 v[4:7], v[8:11], v[120:123], 0
	v_mfma_f32_16x16x32_bf16 v[4:7], v[12:15], v[124:127], v[4:7]
	v_mfma_f32_16x16x32_bf16 v[150:153], v[8:11], v[60:63], 0
	v_mfma_f32_16x16x32_bf16 v[150:153], v[12:15], v[100:103], v[150:153]
	v_mfma_f32_16x16x32_bf16 v[158:161], v[8:11], v[104:107], 0
	v_mfma_f32_16x16x32_bf16 v[158:161], v[12:15], v[108:111], v[158:161]
	v_mfma_f32_16x16x32_bf16 v[166:169], v[8:11], v[112:115], 0
	v_mfma_f32_16x16x32_bf16 v[166:169], v[12:15], v[116:119], v[166:169]
	s_setprio 0
	s_setprio 1
	v_mfma_f32_16x16x32_bf16 v[8:11], v[16:19], v[60:63], 0
	v_mfma_f32_16x16x32_bf16 v[8:11], v[20:23], v[100:103], v[8:11]
	v_mfma_f32_16x16x32_bf16 v[12:15], v[24:27], v[60:63], 0
	v_mfma_f32_16x16x32_bf16 v[12:15], v[28:31], v[100:103], v[12:15]
	v_mfma_f32_16x16x32_bf16 v[60:63], v[16:19], v[104:107], 0
	v_mfma_f32_16x16x32_bf16 v[60:63], v[20:23], v[108:111], v[60:63]
	v_mfma_f32_16x16x32_bf16 v[100:103], v[24:27], v[104:107], 0
	v_mfma_f32_16x16x32_bf16 v[100:103], v[28:31], v[108:111], v[100:103]
	v_mfma_f32_16x16x32_bf16 v[104:107], v[16:19], v[112:115], 0
	v_mfma_f32_16x16x32_bf16 v[104:107], v[20:23], v[116:119], v[104:107]
	v_mfma_f32_16x16x32_bf16 v[16:19], v[16:19], v[120:123], 0
	v_mfma_f32_16x16x32_bf16 v[16:19], v[20:23], v[124:127], v[16:19]
	v_mfma_f32_16x16x32_bf16 v[108:111], v[24:27], v[112:115], 0
	v_mfma_f32_16x16x32_bf16 v[108:111], v[28:31], v[116:119], v[108:111]
	v_mfma_f32_16x16x32_bf16 v[20:23], v[24:27], v[120:123], 0
	v_mfma_f32_16x16x32_bf16 v[20:23], v[28:31], v[124:127], v[20:23]
	s_setprio 0
	s_barrier
	ds_read_b128 v[24:27], v144
	ds_read_b128 v[28:31], v144 offset:1024
	ds_read_b128 v[112:115], v144 offset:2048
	ds_read_b128 v[116:119], v144 offset:3072
	ds_read_b128 v[120:123], v145
	ds_read_b128 v[124:127], v145 offset:1024
	ds_read_b128 v[170:173], v145 offset:2048
	ds_read_b128 v[174:177], v145 offset:3072
	s_add_u32 s60, s26, 0x14000
	s_addc_u32 s61, s27, 0
	s_mov_b32 m0, s39
	ds_read_b128 v[178:181], v143 offset:32768
	ds_read_b128 v[182:185], v143 offset:33792
	ds_read_b128 v[186:189], v143 offset:34816
	ds_read_b128 v[190:193], v143 offset:35840
	ds_read_b128 v[194:197], v143 offset:36864
	ds_read_b128 v[198:201], v143 offset:37888
	ds_read_b128 v[202:205], v143 offset:38912
	ds_read_b128 v[206:209], v143 offset:39936
	global_load_lds_dwordx4 v134, s[60:61]
	v_lshl_add_u64 v[214:215], s[60:61], 0, v[130:131]
	s_mov_b32 m0, s40
	s_nop 0
	global_load_lds_dwordx4 v[214:215], off
	s_waitcnt vmcnt(8)
	s_waitcnt lgkmcnt(0)
	s_barrier
	s_setprio 1
	s_waitcnt lgkmcnt(0)
	v_mfma_f32_16x16x32_bf16 v[64:67], v[24:27], v[178:181], v[64:67]
	v_mfma_f32_16x16x32_bf16 v[64:67], v[28:31], v[182:185], v[64:67]
	v_mfma_f32_16x16x32_bf16 v[68:71], v[116:119], v[182:185], v[68:71]
	v_mfma_f32_16x16x32_bf16 v[68:71], v[112:115], v[178:181], v[68:71]
	v_mfma_f32_16x16x32_bf16 v[76:79], v[112:115], v[186:189], v[76:79]
	v_mfma_f32_16x16x32_bf16 v[76:79], v[116:119], v[190:193], v[76:79]
	v_mfma_f32_16x16x32_bf16 v[72:75], v[28:31], v[190:193], v[72:75]
	v_mfma_f32_16x16x32_bf16 v[72:75], v[24:27], v[186:189], v[72:75]
	v_mfma_f32_16x16x32_bf16 v[80:83], v[24:27], v[194:197], v[80:83]
	v_mfma_f32_16x16x32_bf16 v[80:83], v[28:31], v[198:201], v[80:83]
	v_mfma_f32_16x16x32_bf16 v[84:87], v[116:119], v[198:201], v[84:87]
	v_mfma_f32_16x16x32_bf16 v[84:87], v[112:115], v[194:197], v[84:87]
	v_mfma_f32_16x16x32_bf16 v[92:95], v[112:115], v[202:205], v[92:95]
	v_mfma_f32_16x16x32_bf16 v[92:95], v[116:119], v[206:209], v[92:95]
	v_mfma_f32_16x16x32_bf16 v[88:91], v[28:31], v[206:209], v[88:91]
	v_mfma_f32_16x16x32_bf16 v[88:91], v[24:27], v[202:205], v[88:91]
	s_setprio 0
	s_setprio 1
	v_mfma_f32_16x16x32_bf16 v[96:99], v[120:123], v[178:181], v[96:99]
	v_mfma_f32_16x16x32_bf16 v[96:99], v[124:127], v[182:185], v[96:99]
	v_mfma_f32_16x16x32_bf16 v[32:35], v[174:177], v[182:185], v[32:35]
	v_mfma_f32_16x16x32_bf16 v[32:35], v[170:173], v[178:181], v[32:35]
	v_mfma_f32_16x16x32_bf16 v[40:43], v[170:173], v[186:189], v[40:43]
	v_mfma_f32_16x16x32_bf16 v[40:43], v[174:177], v[190:193], v[40:43]
	v_mfma_f32_16x16x32_bf16 v[36:39], v[124:127], v[190:193], v[36:39]
	v_mfma_f32_16x16x32_bf16 v[36:39], v[120:123], v[186:189], v[36:39]
	v_mfma_f32_16x16x32_bf16 v[44:47], v[120:123], v[194:197], v[44:47]
	v_mfma_f32_16x16x32_bf16 v[44:47], v[124:127], v[198:201], v[44:47]
	v_mfma_f32_16x16x32_bf16 v[48:51], v[174:177], v[198:201], v[48:51]
	v_mfma_f32_16x16x32_bf16 v[48:51], v[170:173], v[194:197], v[48:51]
	v_mfma_f32_16x16x32_bf16 v[56:59], v[170:173], v[202:205], v[56:59]
	v_mfma_f32_16x16x32_bf16 v[56:59], v[174:177], v[206:209], v[56:59]
	v_mfma_f32_16x16x32_bf16 v[52:55], v[124:127], v[206:209], v[52:55]
	v_mfma_f32_16x16x32_bf16 v[52:55], v[120:123], v[202:205], v[52:55]
	s_setprio 0
	s_barrier
; #define PG8_STAGE(bufoff, gbase, voff) do { _Pragma("unroll") for (int _i = 0; _i < 2; ++_i) \
;         __builtin_amdgcn_global_load_lds((const unsigned*)((const char*)(gbase) + (voff)[_i]), (PG8_LAS unsigned*)(lds + (bufoff) + ldsw + _i * 8192), 16, 0, 0); } while (0)
; #define PG8_LDA(dst, b, h) do { _Pragma("unroll") for (int m = 0; m < 4; ++m) _Pragma("unroll") for (int k = 0; k < 2; ++k) dst[m][k] = *(const PG8_LAS bf16x8*)(lds + PG8_SA(b, h) + aoff + m * 2048 + k * 1024); } while (0)
; #define PG8_LDB(dst, b, h) do { _Pragma("unroll") for (int n = 0; n < 2; ++n) _Pragma("unroll") for (int k = 0; k < 2; ++k) dst[n][k] = *(const PG8_LAS bf16x8*)(lds + PG8_SB(b, h) + boff + n * 2048 + k * 1024); } while (0)
; #define PG8_MMA(ai, bj, At, Bt) do { __builtin_amdgcn_s_setprio(1); _Pragma("unroll") for (int m = 0; m < 4; ++m) _Pragma("unroll") for (int n = 0; n < 2; ++n) _Pragma("unroll") for (int k = 0; k < 2; ++k) \
;         acc[ai][bj][m][n] = __builtin_amdgcn_mfma_f32_16x16x32_bf16(Bt[n][k], At[m][k], acc[ai][bj][m][n], 0, 0, 0); __builtin_amdgcn_s_setprio(0); } while (0)
; #define PG8_WAIT_V(n) asm volatile("s_waitcnt vmcnt(" #n ")" ::: "memory")
; #define PG8_WAIT_L(n) asm volatile("s_waitcnt lgkmcnt(" #n ")" ::: "memory")
; #define PG8_BAR __builtin_amdgcn_s_barrier()
; #define PG8_SCHED __builtin_amdgcn_sched_barrier(0)
;     ...
;             PG8_LDB(B0, 0, 0); PG8_LDB(B1, 0, 1); PG8_SCHED; PG8_LDA(At, 0, 0); PG8_STAGE(PG8_SA(1, 1), a1 + hstepA, voffA);
;             PG8_WAIT_V(8); PG8_WAIT_L(0); PG8_BAR; PG8_MMA(0, 0, At, B0); PG8_MMA(0, 1, At, B1); PG8_BAR; PG8_SCHED;
;     ...
;             PG8_LDA(At, 1, 1); PG8_STAGE(PG8_SB(1, 0), b3, voffB); PG8_STAGE(PG8_SB(1, 1), b3 + hstepB, voffB); PG8_STAGE(PG8_SA(1, 0), a3, voffA);
;             PG8_WAIT_V(8); PG8_WAIT_L(0); PG8_BAR; PG8_MMA(1, 0, At, B0); PG8_MMA(1, 1, At, B1); PG8_BAR; PG8_SCHED;
	s_mov_b32 m0, s53
	v_lshl_add_u64 v[210:211], v[210:211], 0, s[18:19]
	s_add_u32 s30, s30, 0x10180
	ds_read_b128 v[178:181], v143 offset:49152
	ds_read_b128 v[182:185], v143 offset:50176
	ds_read_b128 v[186:189], v143 offset:51200
	ds_read_b128 v[190:193], v143 offset:52224
	ds_read_b128 v[194:197], v143 offset:53248
	ds_read_b128 v[198:201], v143 offset:54272
	ds_read_b128 v[202:205], v143 offset:55296
	ds_read_b128 v[206:209], v143 offset:56320
	global_load_lds_dwordx4 v[210:211], off
	v_lshl_add_u64 v[210:211], v[212:213], 0, s[18:19]
	s_mov_b32 m0, s54
	s_addc_u32 s31, s31, 0
	global_load_lds_dwordx4 v[210:211], off
	s_mov_b32 m0, s55
	s_nop 0
	global_load_lds_dwordx4 v132, s[30:31]
	s_mov_b32 m0, s56
	s_nop 0
	global_load_lds_dwordx4 v128, s[30:31]
	s_mov_b32 m0, s42
	s_nop 0
	global_load_lds_dwordx4 v134, s[34:35]
	s_mov_b32 m0, s43
	s_nop 0
	global_load_lds_dwordx4 v130, s[34:35]
	s_waitcnt vmcnt(8)
	s_waitcnt lgkmcnt(0)
	s_barrier
	s_setprio 1
	s_waitcnt lgkmcnt(0)
	v_mfma_f32_16x16x32_bf16 v[0:3], v[24:27], v[202:205], v[0:3]
	v_mfma_f32_16x16x32_bf16 v[0:3], v[28:31], v[206:209], v[0:3]
	v_mfma_f32_16x16x32_bf16 v[4:7], v[116:119], v[206:209], v[4:7]
	v_mfma_f32_16x16x32_bf16 v[4:7], v[112:115], v[202:205], v[4:7]
	v_mfma_f32_16x16x32_bf16 v[150:153], v[112:115], v[178:181], v[150:153]
	v_mfma_f32_16x16x32_bf16 v[150:153], v[116:119], v[182:185], v[150:153]
	v_mfma_f32_16x16x32_bf16 v[146:149], v[28:31], v[182:185], v[146:149]
	v_mfma_f32_16x16x32_bf16 v[146:149], v[24:27], v[178:181], v[146:149]
	v_mfma_f32_16x16x32_bf16 v[154:157], v[24:27], v[186:189], v[154:157]
	v_mfma_f32_16x16x32_bf16 v[154:157], v[28:31], v[190:193], v[154:157]
	v_mfma_f32_16x16x32_bf16 v[158:161], v[116:119], v[190:193], v[158:161]
	v_mfma_f32_16x16x32_bf16 v[158:161], v[112:115], v[186:189], v[158:161]
	v_mfma_f32_16x16x32_bf16 v[166:169], v[112:115], v[194:197], v[166:169]
	v_mfma_f32_16x16x32_bf16 v[166:169], v[116:119], v[198:201], v[166:169]
	v_mfma_f32_16x16x32_bf16 v[162:165], v[28:31], v[198:201], v[162:165]
	v_mfma_f32_16x16x32_bf16 v[162:165], v[24:27], v[194:197], v[162:165]
	s_setprio 0
	s_setprio 1
	v_mfma_f32_16x16x32_bf16 v[8:11], v[120:123], v[178:181], v[8:11]
	v_mfma_f32_16x16x32_bf16 v[8:11], v[124:127], v[182:185], v[8:11]
	v_mfma_f32_16x16x32_bf16 v[12:15], v[170:173], v[178:181], v[12:15]
	v_mfma_f32_16x16x32_bf16 v[12:15], v[174:177], v[182:185], v[12:15]
	v_mfma_f32_16x16x32_bf16 v[24:27], v[120:123], v[186:189], v[60:63]
	v_mfma_f32_16x16x32_bf16 v[24:27], v[124:127], v[190:193], v[24:27]
	v_mfma_f32_16x16x32_bf16 v[28:31], v[170:173], v[186:189], v[100:103]
	v_mfma_f32_16x16x32_bf16 v[28:31], v[174:177], v[190:193], v[28:31]
	v_mfma_f32_16x16x32_bf16 v[60:63], v[120:123], v[194:197], v[104:107]
	v_mfma_f32_16x16x32_bf16 v[60:63], v[124:127], v[198:201], v[60:63]
	v_mfma_f32_16x16x32_bf16 v[100:103], v[170:173], v[194:197], v[108:111]
	v_mfma_f32_16x16x32_bf16 v[100:103], v[174:177], v[198:201], v[100:103]
	v_mfma_f32_16x16x32_bf16 v[16:19], v[120:123], v[202:205], v[16:19]
	v_mfma_f32_16x16x32_bf16 v[16:19], v[124:127], v[206:209], v[16:19]
	v_mfma_f32_16x16x32_bf16 v[20:23], v[170:173], v[202:205], v[20:23]
	v_mfma_f32_16x16x32_bf16 v[20:23], v[174:177], v[206:209], v[20:23]
	s_setprio 0
	s_barrier
	ds_read_b128 v[104:107], v141
	ds_read_b128 v[108:111], v141 offset:1024
	ds_read_b128 v[112:115], v141 offset:2048
	ds_read_b128 v[116:119], v141 offset:3072
	ds_read_b128 v[120:123], v142
	ds_read_b128 v[124:127], v142 offset:1024
	ds_read_b128 v[170:173], v142 offset:2048
	ds_read_b128 v[174:177], v142 offset:3072
	s_add_u32 s30, s28, 0x8000
	s_addc_u32 s31, s29, 0
	s_add_u32 s26, s26, 0x1c000
	s_addc_u32 s27, s27, 0
	s_mov_b32 m0, s46
	ds_read_b128 v[178:181], v143
	ds_read_b128 v[182:185], v143 offset:1024
	ds_read_b128 v[186:189], v143 offset:2048
	ds_read_b128 v[190:193], v143 offset:3072
	ds_read_b128 v[194:197], v143 offset:4096
	ds_read_b128 v[198:201], v143 offset:5120
	ds_read_b128 v[202:205], v143 offset:6144
	ds_read_b128 v[206:209], v143 offset:7168
	global_load_lds_dwordx4 v134, s[26:27]
	v_lshl_add_u64 v[210:211], s[26:27], 0, v[130:131]
	s_mov_b32 m0, s47
	s_nop 0
	global_load_lds_dwordx4 v[210:211], off
	s_waitcnt vmcnt(8)
	s_waitcnt lgkmcnt(0)
	s_barrier
	s_setprio 1
	s_waitcnt lgkmcnt(0)
	v_mfma_f32_16x16x32_bf16 v[64:67], v[104:107], v[178:181], v[64:67]
	v_mfma_f32_16x16x32_bf16 v[64:67], v[108:111], v[182:185], v[64:67]
	v_mfma_f32_16x16x32_bf16 v[68:71], v[112:115], v[178:181], v[68:71]
	v_mfma_f32_16x16x32_bf16 v[68:71], v[116:119], v[182:185], v[68:71]
	v_mfma_f32_16x16x32_bf16 v[72:75], v[104:107], v[186:189], v[72:75]
	v_mfma_f32_16x16x32_bf16 v[72:75], v[108:111], v[190:193], v[72:75]
	v_mfma_f32_16x16x32_bf16 v[76:79], v[112:115], v[186:189], v[76:79]
	v_mfma_f32_16x16x32_bf16 v[76:79], v[116:119], v[190:193], v[76:79]
	v_mfma_f32_16x16x32_bf16 v[80:83], v[104:107], v[194:197], v[80:83]
	v_mfma_f32_16x16x32_bf16 v[80:83], v[108:111], v[198:201], v[80:83]
	v_mfma_f32_16x16x32_bf16 v[84:87], v[112:115], v[194:197], v[84:87]
	v_mfma_f32_16x16x32_bf16 v[84:87], v[116:119], v[198:201], v[84:87]
	v_mfma_f32_16x16x32_bf16 v[88:91], v[104:107], v[202:205], v[88:91]
	v_mfma_f32_16x16x32_bf16 v[210:213], v[108:111], v[206:209], v[88:91]
	v_mfma_f32_16x16x32_bf16 v[88:91], v[112:115], v[202:205], v[92:95]
	v_mfma_f32_16x16x32_bf16 v[214:217], v[116:119], v[206:209], v[88:91]
	s_setprio 0
	s_setprio 1
	v_mfma_f32_16x16x32_bf16 v[88:91], v[120:123], v[178:181], v[96:99]
	v_mfma_f32_16x16x32_bf16 v[96:99], v[124:127], v[182:185], v[88:91]
	v_mfma_f32_16x16x32_bf16 v[32:35], v[170:173], v[178:181], v[32:35]
	v_mfma_f32_16x16x32_bf16 v[32:35], v[174:177], v[182:185], v[32:35]
	v_mfma_f32_16x16x32_bf16 v[36:39], v[120:123], v[186:189], v[36:39]
	v_mfma_f32_16x16x32_bf16 v[36:39], v[124:127], v[190:193], v[36:39]
	v_mfma_f32_16x16x32_bf16 v[40:43], v[170:173], v[186:189], v[40:43]
	v_mfma_f32_16x16x32_bf16 v[40:43], v[174:177], v[190:193], v[40:43]
	v_mfma_f32_16x16x32_bf16 v[44:47], v[120:123], v[194:197], v[44:47]
	v_mfma_f32_16x16x32_bf16 v[44:47], v[124:127], v[198:201], v[44:47]
	v_mfma_f32_16x16x32_bf16 v[48:51], v[170:173], v[194:197], v[48:51]
	v_mfma_f32_16x16x32_bf16 v[48:51], v[174:177], v[198:201], v[48:51]
	v_mfma_f32_16x16x32_bf16 v[52:55], v[120:123], v[202:205], v[52:55]
	v_mfma_f32_16x16x32_bf16 v[52:55], v[124:127], v[206:209], v[52:55]
	v_mfma_f32_16x16x32_bf16 v[56:59], v[170:173], v[202:205], v[56:59]
	v_mfma_f32_16x16x32_bf16 v[56:59], v[174:177], v[206:209], v[56:59]
	s_setprio 0
	s_barrier
; #define PG8_STAGE(bufoff, gbase, voff) do { _Pragma("unroll") for (int _i = 0; _i < 2; ++_i) \
;         __builtin_amdgcn_global_load_lds((const unsigned*)((const char*)(gbase) + (voff)[_i]), (PG8_LAS unsigned*)(lds + (bufoff) + ldsw + _i * 8192), 16, 0, 0); } while (0)
; #define PG8_LDA(dst, b, h) do { _Pragma("unroll") for (int m = 0; m < 4; ++m) _Pragma("unroll") for (int k = 0; k < 2; ++k) dst[m][k] = *(const PG8_LAS bf16x8*)(lds + PG8_SA(b, h) + aoff + m * 2048 + k * 1024); } while (0)
; #define PG8_LDB(dst, b, h) do { _Pragma("unroll") for (int n = 0; n < 2; ++n) _Pragma("unroll") for (int k = 0; k < 2; ++k) dst[n][k] = *(const PG8_LAS bf16x8*)(lds + PG8_SB(b, h) + boff + n * 2048 + k * 1024); } while (0)
; #define PG8_MMA(ai, bj, At, Bt) do { __builtin_amdgcn_s_setprio(1); _Pragma("unroll") for (int m = 0; m < 4; ++m) _Pragma("unroll") for (int n = 0; n < 2; ++n) _Pragma("unroll") for (int k = 0; k < 2; ++k) \
;         acc[ai][bj][m][n] = __builtin_amdgcn_mfma_f32_16x16x32_bf16(Bt[n][k], At[m][k], acc[ai][bj][m][n], 0, 0, 0); __builtin_amdgcn_s_setprio(0); } while (0)
; #define PG8_WAIT_V(n) asm volatile("s_waitcnt vmcnt(" #n ")" ::: "memory")
; #define PG8_WAIT_L(n) asm volatile("s_waitcnt lgkmcnt(" #n ")" ::: "memory")
; #define PG8_BAR __builtin_amdgcn_s_barrier()
; #define PG8_SCHED __builtin_amdgcn_sched_barrier(0)
;     ...
;             PG8_LDA(At, 0, 1); PG8_STAGE(PG8_SB(0, 0), b2, voffB); PG8_STAGE(PG8_SB(0, 1), b2 + hstepB, voffB); PG8_STAGE(PG8_SA(0, 0), a2, voffA);
;             PG8_WAIT_V(8); PG8_WAIT_L(0); PG8_BAR; PG8_MMA(1, 0, At, B0); PG8_MMA(1, 1, At, B1); PG8_BAR; PG8_SCHED;
;             PG8_LDB(B0, 1, 0); PG8_LDB(B1, 1, 1); PG8_SCHED; PG8_LDA(At, 1, 0); PG8_STAGE(PG8_SA(0, 1), a2 + hstepA, voffA);
;             PG8_WAIT_V(8); PG8_WAIT_L(0); PG8_BAR; PG8_MMA(0, 0, At, B0); PG8_MMA(0, 1, At, B1); PG8_BAR; PG8_SCHED;
	s_mov_b32 m0, s48
	v_lshl_add_u64 v[246:247], s[24:25], 0, v[132:133]
	s_add_u32 s26, s24, 0x10000
	ds_read_b128 v[88:91], v143 offset:16384
	ds_read_b128 v[92:95], v143 offset:17408
	ds_read_b128 v[178:181], v143 offset:18432
	ds_read_b128 v[182:185], v143 offset:19456
	ds_read_b128 v[186:189], v143 offset:20480
	ds_read_b128 v[190:193], v143 offset:21504
	ds_read_b128 v[194:197], v143 offset:22528
	ds_read_b128 v[198:201], v143 offset:23552
	global_load_lds_dwordx4 v[246:247], off
	v_lshl_add_u64 v[248:249], s[24:25], 0, v[128:129]
	s_mov_b32 m0, s50
	s_addc_u32 s27, s25, 0
	global_load_lds_dwordx4 v[248:249], off
	s_mov_b32 m0, s51
	s_nop 0
	global_load_lds_dwordx4 v132, s[26:27]
	s_mov_b32 m0, s52
	s_nop 0
	global_load_lds_dwordx4 v128, s[26:27]
	s_mov_b32 m0, s23
	s_nop 0
	global_load_lds_dwordx4 v134, s[28:29]
	v_lshl_add_u64 v[202:203], s[28:29], 0, v[130:131]
	s_mov_b32 m0, s37
	s_nop 0
	global_load_lds_dwordx4 v[202:203], off
	s_waitcnt vmcnt(8)
	s_waitcnt lgkmcnt(0)
	s_barrier
	s_setprio 1
	s_waitcnt lgkmcnt(0)
	v_mfma_f32_16x16x32_bf16 v[0:3], v[104:107], v[194:197], v[0:3]
	v_mfma_f32_16x16x32_bf16 v[0:3], v[108:111], v[198:201], v[0:3]
	v_mfma_f32_16x16x32_bf16 v[4:7], v[116:119], v[198:201], v[4:7]
	v_mfma_f32_16x16x32_bf16 v[4:7], v[112:115], v[194:197], v[4:7]
	v_mfma_f32_16x16x32_bf16 v[150:153], v[112:115], v[88:91], v[150:153]
	v_mfma_f32_16x16x32_bf16 v[150:153], v[116:119], v[92:95], v[150:153]
	v_mfma_f32_16x16x32_bf16 v[146:149], v[108:111], v[92:95], v[146:149]
	v_mfma_f32_16x16x32_bf16 v[146:149], v[104:107], v[88:91], v[146:149]
	v_mfma_f32_16x16x32_bf16 v[154:157], v[104:107], v[178:181], v[154:157]
	v_mfma_f32_16x16x32_bf16 v[154:157], v[108:111], v[182:185], v[154:157]
	v_mfma_f32_16x16x32_bf16 v[158:161], v[116:119], v[182:185], v[158:161]
	v_mfma_f32_16x16x32_bf16 v[158:161], v[112:115], v[178:181], v[158:161]
	v_mfma_f32_16x16x32_bf16 v[166:169], v[112:115], v[186:189], v[166:169]
	v_mfma_f32_16x16x32_bf16 v[166:169], v[116:119], v[190:193], v[166:169]
	v_mfma_f32_16x16x32_bf16 v[162:165], v[108:111], v[190:193], v[162:165]
	v_mfma_f32_16x16x32_bf16 v[162:165], v[104:107], v[186:189], v[162:165]
	s_setprio 0
	s_setprio 1
	v_mfma_f32_16x16x32_bf16 v[8:11], v[120:123], v[88:91], v[8:11]
	v_mfma_f32_16x16x32_bf16 v[202:205], v[124:127], v[92:95], v[8:11]
	v_mfma_f32_16x16x32_bf16 v[8:11], v[170:173], v[88:91], v[12:15]
	v_mfma_f32_16x16x32_bf16 v[206:209], v[174:177], v[92:95], v[8:11]
	v_mfma_f32_16x16x32_bf16 v[8:11], v[120:123], v[178:181], v[24:27]
	v_mfma_f32_16x16x32_bf16 v[218:221], v[124:127], v[182:185], v[8:11]
	v_mfma_f32_16x16x32_bf16 v[8:11], v[170:173], v[178:181], v[28:31]
	v_mfma_f32_16x16x32_bf16 v[178:181], v[174:177], v[182:185], v[8:11]
	v_mfma_f32_16x16x32_bf16 v[8:11], v[120:123], v[186:189], v[60:63]
	v_mfma_f32_16x16x32_bf16 v[182:185], v[124:127], v[190:193], v[8:11]
	v_mfma_f32_16x16x32_bf16 v[8:11], v[170:173], v[186:189], v[100:103]
	v_mfma_f32_16x16x32_bf16 v[186:189], v[174:177], v[190:193], v[8:11]
	v_mfma_f32_16x16x32_bf16 v[8:11], v[120:123], v[194:197], v[16:19]
	v_mfma_f32_16x16x32_bf16 v[190:193], v[124:127], v[198:201], v[8:11]
	v_mfma_f32_16x16x32_bf16 v[8:11], v[170:173], v[194:197], v[20:23]
	v_mfma_f32_16x16x32_bf16 v[170:173], v[174:177], v[198:201], v[8:11]
	s_setprio 0
	s_barrier
	s_nop 4
	ds_read_b128 v[8:11], v144
	ds_read_b128 v[12:15], v144 offset:1024
	ds_read_b128 v[16:19], v144 offset:2048
	ds_read_b128 v[20:23], v144 offset:3072
	ds_read_b128 v[174:177], v145
	ds_read_b128 v[194:197], v145 offset:1024
	ds_read_b128 v[198:201], v145 offset:2048
	ds_read_b128 v[222:225], v145 offset:3072
	s_add_u32 s26, s28, 0x4000
	s_addc_u32 s27, s29, 0
	s_mov_b32 m0, s39
	ds_read_b128 v[24:27], v143 offset:32768
	ds_read_b128 v[28:31], v143 offset:33792
	ds_read_b128 v[60:63], v143 offset:34816
	ds_read_b128 v[226:229], v143 offset:35840
	ds_read_b128 v[230:233], v143 offset:36864
	ds_read_b128 v[234:237], v143 offset:37888
	ds_read_b128 v[238:241], v143 offset:38912
	ds_read_b128 v[242:245], v143 offset:39936
	global_load_lds_dwordx4 v134, s[26:27]
	v_lshl_add_u64 v[88:89], s[26:27], 0, v[130:131]
	s_mov_b32 m0, s40
	s_nop 0
	global_load_lds_dwordx4 v[88:89], off
	s_waitcnt vmcnt(8)
	s_waitcnt lgkmcnt(0)
	s_barrier
; #define PG8_STAGE(bufoff, gbase, voff) do { _Pragma("unroll") for (int _i = 0; _i < 2; ++_i) \
;         __builtin_amdgcn_global_load_lds((const unsigned*)((const char*)(gbase) + (voff)[_i]), (PG8_LAS unsigned*)(lds + (bufoff) + ldsw + _i * 8192), 16, 0, 0); } while (0)
; #define PG8_LDA(dst, b, h) do { _Pragma("unroll") for (int m = 0; m < 4; ++m) _Pragma("unroll") for (int k = 0; k < 2; ++k) dst[m][k] = *(const PG8_LAS bf16x8*)(lds + PG8_SA(b, h) + aoff + m * 2048 + k * 1024); } while (0)
; #define PG8_MMA(ai, bj, At, Bt) do { __builtin_amdgcn_s_setprio(1); _Pragma("unroll") for (int m = 0; m < 4; ++m) _Pragma("unroll") for (int n = 0; n < 2; ++n) _Pragma("unroll") for (int k = 0; k < 2; ++k) \
;         acc[ai][bj][m][n] = __builtin_amdgcn_mfma_f32_16x16x32_bf16(Bt[n][k], At[m][k], acc[ai][bj][m][n], 0, 0, 0); __builtin_amdgcn_s_setprio(0); } while (0)
; #define PG8_WAIT_V(n) asm volatile("s_waitcnt vmcnt(" #n ")" ::: "memory")
; #define PG8_WAIT_L(n) asm volatile("s_waitcnt lgkmcnt(" #n ")" ::: "memory")
; #define PG8_BAR __builtin_amdgcn_s_barrier()
; #define PG8_SCHED __builtin_amdgcn_sched_barrier(0)
;     ...
;             PG8_WAIT_V(8); PG8_WAIT_L(0); PG8_BAR; PG8_MMA(0, 0, At, B0); PG8_MMA(0, 1, At, B1); PG8_BAR; PG8_SCHED;
;             PG8_LDA(At, 1, 1); PG8_STAGE(PG8_SB(1, 0), b3, voffB); PG8_STAGE(PG8_SB(1, 1), b3 + hstepB, voffB); PG8_STAGE(PG8_SA(1, 0), a3, voffA);
;             PG8_WAIT_V(8); PG8_WAIT_L(0); PG8_BAR; PG8_MMA(1, 0, At, B0); PG8_MMA(1, 1, At, B1); PG8_BAR; PG8_SCHED;
;     ...
;         if constexpr (ALIGN_EPI) { if (wr == 0) PG8_BAR; }
	s_setprio 1
	s_waitcnt lgkmcnt(0)
	v_mfma_f32_16x16x32_bf16 v[64:67], v[8:11], v[24:27], v[64:67]
	v_mfma_f32_16x16x32_bf16 v[124:127], v[12:15], v[28:31], v[64:67]
	v_mfma_f32_16x16x32_bf16 v[64:67], v[16:19], v[24:27], v[68:71]
	v_mfma_f32_16x16x32_bf16 v[120:123], v[20:23], v[28:31], v[64:67]
	v_mfma_f32_16x16x32_bf16 v[64:67], v[8:11], v[60:63], v[72:75]
	v_mfma_f32_16x16x32_bf16 v[108:111], v[12:15], v[226:229], v[64:67]
	v_mfma_f32_16x16x32_bf16 v[64:67], v[16:19], v[60:63], v[76:79]
	v_mfma_f32_16x16x32_bf16 v[104:107], v[20:23], v[226:229], v[64:67]
	v_mfma_f32_16x16x32_bf16 v[64:67], v[8:11], v[230:233], v[80:83]
	v_mfma_f32_16x16x32_bf16 v[92:95], v[12:15], v[234:237], v[64:67]
	v_mfma_f32_16x16x32_bf16 v[64:67], v[16:19], v[230:233], v[84:87]
	v_mfma_f32_16x16x32_bf16 v[88:91], v[20:23], v[234:237], v[64:67]
	v_mfma_f32_16x16x32_bf16 v[64:67], v[8:11], v[238:241], v[210:213]
	v_mfma_f32_16x16x32_bf16 v[76:79], v[12:15], v[242:245], v[64:67]
	v_mfma_f32_16x16x32_bf16 v[64:67], v[16:19], v[238:241], v[214:217]
	v_mfma_f32_16x16x32_bf16 v[72:75], v[20:23], v[242:245], v[64:67]
	s_setprio 0
	s_setprio 1
	v_mfma_f32_16x16x32_bf16 v[64:67], v[174:177], v[24:27], v[96:99]
	v_mfma_f32_16x16x32_bf16 v[24:27], v[198:201], v[24:27], v[32:35]
	v_mfma_f32_16x16x32_bf16 v[112:115], v[222:225], v[28:31], v[24:27]
	v_mfma_f32_16x16x32_bf16 v[24:27], v[174:177], v[60:63], v[36:39]
	v_mfma_f32_16x16x32_bf16 v[100:103], v[194:197], v[226:229], v[24:27]
	v_mfma_f32_16x16x32_bf16 v[24:27], v[198:201], v[60:63], v[40:43]
	v_mfma_f32_16x16x32_bf16 v[96:99], v[222:225], v[226:229], v[24:27]
	v_mfma_f32_16x16x32_bf16 v[24:27], v[174:177], v[230:233], v[44:47]
	v_mfma_f32_16x16x32_bf16 v[84:87], v[194:197], v[234:237], v[24:27]
	v_mfma_f32_16x16x32_bf16 v[24:27], v[198:201], v[230:233], v[48:51]
	v_mfma_f32_16x16x32_bf16 v[80:83], v[222:225], v[234:237], v[24:27]
	v_mfma_f32_16x16x32_bf16 v[24:27], v[174:177], v[238:241], v[52:55]
	v_mfma_f32_16x16x32_bf16 v[60:63], v[194:197], v[242:245], v[24:27]
	v_mfma_f32_16x16x32_bf16 v[24:27], v[198:201], v[238:241], v[56:59]
	v_mfma_f32_16x16x32_bf16 v[116:119], v[194:197], v[28:31], v[64:67]
	v_mfma_f32_16x16x32_bf16 v[56:59], v[222:225], v[242:245], v[24:27]
	s_setprio 0
	s_barrier
	s_mov_b32 m0, s53
	s_nop 2
	v_lshl_add_u64 v[24:25], v[246:247], 0, s[12:13]
	s_add_u32 s24, s24, 0x10080
	ds_read_b128 v[32:35], v143 offset:49152
	ds_read_b128 v[36:39], v143 offset:50176
	ds_read_b128 v[210:213], v143 offset:51200
	ds_read_b128 v[214:217], v143 offset:52224
	ds_read_b128 v[226:229], v143 offset:53248
	ds_read_b128 v[230:233], v143 offset:54272
	ds_read_b128 v[234:237], v143 offset:55296
	ds_read_b128 v[238:241], v143 offset:56320
	global_load_lds_dwordx4 v[24:25], off
	v_lshl_add_u64 v[24:25], v[248:249], 0, s[12:13]
	s_mov_b32 m0, s54
	s_addc_u32 s25, s25, 0
	global_load_lds_dwordx4 v[24:25], off
	s_mov_b32 m0, s55
	s_nop 0
	global_load_lds_dwordx4 v132, s[24:25]
	s_mov_b32 m0, s56
	s_nop 0
	global_load_lds_dwordx4 v128, s[24:25]
	s_mov_b32 m0, s42
	s_nop 0
	global_load_lds_dwordx4 v134, s[30:31]
	v_lshl_add_u64 v[24:25], s[30:31], 0, v[130:131]
	s_mov_b32 m0, s43
	s_nop 0
	global_load_lds_dwordx4 v[24:25], off
	s_waitcnt vmcnt(8)
	s_waitcnt lgkmcnt(0)
	s_barrier
	s_setprio 1
	s_waitcnt lgkmcnt(0)
	v_mfma_f32_16x16x32_bf16 v[24:27], v[8:11], v[32:35], v[146:149]
	v_mfma_f32_16x16x32_bf16 v[68:71], v[12:15], v[36:39], v[24:27]
	v_mfma_f32_16x16x32_bf16 v[24:27], v[16:19], v[32:35], v[150:153]
	v_mfma_f32_16x16x32_bf16 v[64:67], v[20:23], v[36:39], v[24:27]
	v_mfma_f32_16x16x32_bf16 v[24:27], v[8:11], v[210:213], v[154:157]
	v_mfma_f32_16x16x32_bf16 v[44:47], v[12:15], v[214:217], v[24:27]
	v_mfma_f32_16x16x32_bf16 v[24:27], v[16:19], v[210:213], v[158:161]
	v_mfma_f32_16x16x32_bf16 v[40:43], v[20:23], v[214:217], v[24:27]
	v_mfma_f32_16x16x32_bf16 v[24:27], v[8:11], v[226:229], v[162:165]
	v_mfma_f32_16x16x32_bf16 v[28:31], v[12:15], v[230:233], v[24:27]
	v_mfma_f32_16x16x32_bf16 v[0:3], v[8:11], v[234:237], v[0:3]
	v_mfma_f32_16x16x32_bf16 v[12:15], v[12:15], v[238:241], v[0:3]
	v_mfma_f32_16x16x32_bf16 v[24:27], v[16:19], v[226:229], v[166:169]
	v_mfma_f32_16x16x32_bf16 v[24:27], v[20:23], v[230:233], v[24:27]
	v_mfma_f32_16x16x32_bf16 v[0:3], v[16:19], v[234:237], v[4:7]
	v_mfma_f32_16x16x32_bf16 v[8:11], v[20:23], v[238:241], v[0:3]
	s_setprio 0
	s_setprio 1
	v_mfma_f32_16x16x32_bf16 v[0:3], v[174:177], v[32:35], v[202:205]
	v_mfma_f32_16x16x32_bf16 v[52:55], v[194:197], v[36:39], v[0:3]
	v_mfma_f32_16x16x32_bf16 v[0:3], v[198:201], v[32:35], v[206:209]
	v_mfma_f32_16x16x32_bf16 v[48:51], v[222:225], v[36:39], v[0:3]
	v_mfma_f32_16x16x32_bf16 v[0:3], v[174:177], v[210:213], v[218:221]
	v_mfma_f32_16x16x32_bf16 v[36:39], v[194:197], v[214:217], v[0:3]
	v_mfma_f32_16x16x32_bf16 v[0:3], v[198:201], v[210:213], v[178:181]
	v_mfma_f32_16x16x32_bf16 v[32:35], v[222:225], v[214:217], v[0:3]
	v_mfma_f32_16x16x32_bf16 v[0:3], v[174:177], v[226:229], v[182:185]
	v_mfma_f32_16x16x32_bf16 v[20:23], v[194:197], v[230:233], v[0:3]
	v_mfma_f32_16x16x32_bf16 v[0:3], v[198:201], v[226:229], v[186:189]
	v_mfma_f32_16x16x32_bf16 v[16:19], v[222:225], v[230:233], v[0:3]
	v_mfma_f32_16x16x32_bf16 v[0:3], v[174:177], v[234:237], v[190:193]
	v_mfma_f32_16x16x32_bf16 v[4:7], v[194:197], v[238:241], v[0:3]
	v_mfma_f32_16x16x32_bf16 v[0:3], v[198:201], v[234:237], v[170:173]
	v_mfma_f32_16x16x32_bf16 v[0:3], v[222:225], v[238:241], v[0:3]
	s_setprio 0
	s_barrier
	s_and_b64 vcc, exec, s[0:1]
	s_cbranch_vccnz .LBB0_99
	s_barrier

; #define PG8_STAGE(bufoff, gbase, voff) do { _Pragma("unroll") for (int _i = 0; _i < 2; ++_i) \
;         __builtin_amdgcn_global_load_lds((const unsigned*)((const char*)(gbase) + (voff)[_i]), (PG8_LAS unsigned*)(lds + (bufoff) + ldsw + _i * 8192), 16, 0, 0); } while (0)
; #define PG8_LDA(dst, b, h) do { _Pragma("unroll") for (int m = 0; m < 4; ++m) _Pragma("unroll") for (int k = 0; k < 2; ++k) dst[m][k] = *(const PG8_LAS bf16x8*)(lds + PG8_SA(b, h) + aoff + m * 2048 + k * 1024); } while (0)
; #define PG8_LDB(dst, b, h) do { _Pragma("unroll") for (int n = 0; n < 2; ++n) _Pragma("unroll") for (int k = 0; k < 2; ++k) dst[n][k] = *(const PG8_LAS bf16x8*)(lds + PG8_SB(b, h) + boff + n * 2048 + k * 1024); } while (0)
; #define PG8_MMA(ai, bj, At, Bt) do { __builtin_amdgcn_s_setprio(1); _Pragma("unroll") for (int m = 0; m < 4; ++m) _Pragma("unroll") for (int n = 0; n < 2; ++n) _Pragma("unroll") for (int k = 0; k < 2; ++k) \
;         acc[ai][bj][m][n] = __builtin_amdgcn_mfma_f32_16x16x32_bf16(Bt[n][k], At[m][k], acc[ai][bj][m][n], 0, 0, 0); __builtin_amdgcn_s_setprio(0); } while (0)
; #define PG8_WAIT_V(n) asm volatile("s_waitcnt vmcnt(" #n ")" ::: "memory")
; #define PG8_WAIT_L(n) asm volatile("s_waitcnt lgkmcnt(" #n ")" ::: "memory")
; #define PG8_BAR __builtin_amdgcn_s_barrier()
; #define PG8_SCHED __builtin_amdgcn_sched_barrier(0)
;     ...
;         for (int t = 0; t < nt; t += 2) {
;             const bool last = (t == nt - 2);
;             const char* a1 = cA + (ptrdiff_t)(t + 1) * kstepA;
;             const char* a2 = last ? nA : cA + (ptrdiff_t)(t + 2) * kstepA; const char* b2 = last ? nB : cB + (ptrdiff_t)(t + 2) * kstep;
;             const char* a3 = a2 + kstepA; const char* b3 = b2 + kstep;
;             if (last && has_next) S.a_ready(nxt);
;             if constexpr (SP2) {
;             PG8_LDB(B0, 0, 0); PG8_LDB(B1, 0, 1); PG8_SCHED; PG8_LDA(At, 0, 0); PG8_STAGE(PG8_SA(1, 1), a1 + hstepA, voffA);
;             PG8_WAIT_V(8); PG8_WAIT_L(0); PG8_BAR; PG8_MMA(0, 0, At, B0); PG8_MMA(0, 1, At, B1); PG8_BAR; PG8_SCHED;
;             PG8_LDA(At, 0, 1); PG8_STAGE(PG8_SB(0, 0), b2, voffB); PG8_STAGE(PG8_SB(0, 1), b2 + hstepB, voffB); PG8_STAGE(PG8_SA(0, 0), a2, voffA);
;             PG8_WAIT_V(8); PG8_WAIT_L(0); PG8_BAR; PG8_MMA(1, 0, At, B0); PG8_MMA(1, 1, At, B1); PG8_BAR; PG8_SCHED;
.LBB0_328:
	s_add_u32 s65, s6, 0x4000
	s_addc_u32 s66, s7, 0
	s_cmp_eq_u32 vcc_lo, 28
	s_cselect_b32 s90, s54, s65
	s_cselect_b32 s91, s29, s66
	s_cselect_b32 s88, s55, s56
	s_cselect_b32 s89, s31, s57
	s_add_u32 s86, s90, 0x8000
	s_addc_u32 s87, s91, 0
	s_add_i32 s65, 0, 0x10000
	s_add_i32 s66, 0, 0x14000
	v_add_u32_e32 v22, s65, v182
	v_add_u32_e32 v54, s66, v182
	ds_read_b128 v[10:13], v22
	ds_read_b128 v[14:17], v22 offset:1024
	ds_read_b128 v[18:21], v22 offset:2048
	ds_read_b128 v[22:25], v22 offset:3072
	ds_read_b128 v[26:29], v54
	ds_read_b128 v[38:41], v54 offset:1024
	ds_read_b128 v[50:53], v54 offset:2048
	ds_read_b128 v[54:57], v54 offset:3072
	s_add_i32 m0, s51, 0xc000
	ds_read_b128 v[172:175], v183
	ds_read_b128 v[176:179], v183 offset:1024
	ds_read_b128 v[184:187], v183 offset:2048
	ds_read_b128 v[188:191], v183 offset:3072
	ds_read_b128 v[192:195], v183 offset:4096
	ds_read_b128 v[196:199], v183 offset:5120
	ds_read_b128 v[200:203], v183 offset:6144
	ds_read_b128 v[204:207], v183 offset:7168
	global_load_lds_dwordx4 v168, s[6:7]
	s_add_i32 m0, s51, 0xe000
	s_nop 0
	global_load_lds_dwordx4 v170, s[6:7]
	s_waitcnt vmcnt(8)
	s_waitcnt lgkmcnt(0)
	s_barrier
	s_setprio 1
	s_waitcnt lgkmcnt(0)
	v_mfma_f32_16x16x32_bf16 v[158:161], v[10:13], v[172:175], v[158:161]
	v_mfma_f32_16x16x32_bf16 v[158:161], v[14:17], v[176:179], v[158:161]
	v_mfma_f32_16x16x32_bf16 v[154:157], v[22:25], v[176:179], v[154:157]
	v_mfma_f32_16x16x32_bf16 v[154:157], v[18:21], v[172:175], v[154:157]
	v_mfma_f32_16x16x32_bf16 v[138:141], v[18:21], v[184:187], v[138:141]
	v_mfma_f32_16x16x32_bf16 v[138:141], v[22:25], v[188:191], v[138:141]
	v_mfma_f32_16x16x32_bf16 v[142:145], v[14:17], v[188:191], v[142:145]
	v_mfma_f32_16x16x32_bf16 v[142:145], v[10:13], v[184:187], v[142:145]
	v_mfma_f32_16x16x32_bf16 v[126:129], v[10:13], v[192:195], v[126:129]
	v_mfma_f32_16x16x32_bf16 v[126:129], v[14:17], v[196:199], v[126:129]
	v_mfma_f32_16x16x32_bf16 v[122:125], v[22:25], v[196:199], v[122:125]
	v_mfma_f32_16x16x32_bf16 v[122:125], v[18:21], v[192:195], v[122:125]
	v_mfma_f32_16x16x32_bf16 v[106:109], v[18:21], v[200:203], v[106:109]
	v_mfma_f32_16x16x32_bf16 v[106:109], v[22:25], v[204:207], v[106:109]
	v_mfma_f32_16x16x32_bf16 v[110:113], v[14:17], v[204:207], v[110:113]
	v_mfma_f32_16x16x32_bf16 v[110:113], v[10:13], v[200:203], v[110:113]
	s_setprio 0
	s_setprio 1
	v_mfma_f32_16x16x32_bf16 v[150:153], v[26:29], v[172:175], v[150:153]
	v_mfma_f32_16x16x32_bf16 v[150:153], v[38:41], v[176:179], v[150:153]
	v_mfma_f32_16x16x32_bf16 v[146:149], v[54:57], v[176:179], v[146:149]
	v_mfma_f32_16x16x32_bf16 v[146:149], v[50:53], v[172:175], v[146:149]
	v_mfma_f32_16x16x32_bf16 v[130:133], v[50:53], v[184:187], v[130:133]
	v_mfma_f32_16x16x32_bf16 v[130:133], v[54:57], v[188:191], v[130:133]
	v_mfma_f32_16x16x32_bf16 v[134:137], v[38:41], v[188:191], v[134:137]
	v_mfma_f32_16x16x32_bf16 v[134:137], v[26:29], v[184:187], v[134:137]
	v_mfma_f32_16x16x32_bf16 v[118:121], v[26:29], v[192:195], v[118:121]
	v_mfma_f32_16x16x32_bf16 v[118:121], v[38:41], v[196:199], v[118:121]
	v_mfma_f32_16x16x32_bf16 v[114:117], v[54:57], v[196:199], v[114:117]
	v_mfma_f32_16x16x32_bf16 v[114:117], v[50:53], v[192:195], v[114:117]
	v_mfma_f32_16x16x32_bf16 v[98:101], v[50:53], v[200:203], v[98:101]
	v_mfma_f32_16x16x32_bf16 v[98:101], v[54:57], v[204:207], v[98:101]
	v_mfma_f32_16x16x32_bf16 v[102:105], v[38:41], v[204:207], v[102:105]
	v_mfma_f32_16x16x32_bf16 v[102:105], v[26:29], v[200:203], v[102:105]
	s_setprio 0
	s_barrier
	s_add_i32 s65, s65, s2
	s_mov_b32 m0, s65
	ds_read_b128 v[172:175], v183 offset:16384
	ds_read_b128 v[176:179], v183 offset:17408
	ds_read_b128 v[184:187], v183 offset:18432
	ds_read_b128 v[188:191], v183 offset:19456
	ds_read_b128 v[192:195], v183 offset:20480
	ds_read_b128 v[196:199], v183 offset:21504
	ds_read_b128 v[200:203], v183 offset:22528
	ds_read_b128 v[204:207], v183 offset:23552
	global_load_lds_dwordx4 v0, s[88:89]
	s_add_i32 m0, s65, 0x2000
	s_add_u32 s96, s88, 0x4000
	s_addc_u32 s97, s89, 0
	s_add_i32 s65, s66, s2
	global_load_lds_dwordx4 v162, s[88:89]
	s_mov_b32 m0, s65
	s_nop 0
	global_load_lds_dwordx4 v0, s[96:97]
	s_add_i32 m0, s65, 0x2000
	s_nop 0
	global_load_lds_dwordx4 v162, s[96:97]
	s_mov_b32 m0, s51
	s_nop 0
	global_load_lds_dwordx4 v166, s[90:91]
	s_mov_b32 m0, s92
	s_nop 0
	global_load_lds_dwordx4 v164, s[90:91]
	s_waitcnt vmcnt(8)
	s_waitcnt lgkmcnt(0)
	s_barrier
	s_setprio 1
	s_waitcnt lgkmcnt(0)
	v_mfma_f32_16x16x32_bf16 v[94:97], v[10:13], v[172:175], v[94:97]
	v_mfma_f32_16x16x32_bf16 v[94:97], v[14:17], v[176:179], v[94:97]
	v_mfma_f32_16x16x32_bf16 v[90:93], v[18:21], v[172:175], v[90:93]
	v_mfma_f32_16x16x32_bf16 v[90:93], v[22:25], v[176:179], v[90:93]
	v_mfma_f32_16x16x32_bf16 v[78:81], v[10:13], v[184:187], v[78:81]
	v_mfma_f32_16x16x32_bf16 v[78:81], v[14:17], v[188:191], v[78:81]
	v_mfma_f32_16x16x32_bf16 v[74:77], v[18:21], v[184:187], v[74:77]
	v_mfma_f32_16x16x32_bf16 v[74:77], v[22:25], v[188:191], v[74:77]
	v_mfma_f32_16x16x32_bf16 v[62:65], v[10:13], v[192:195], v[62:65]
	v_mfma_f32_16x16x32_bf16 v[62:65], v[14:17], v[196:199], v[62:65]
	v_mfma_f32_16x16x32_bf16 v[58:61], v[18:21], v[192:195], v[58:61]
	v_mfma_f32_16x16x32_bf16 v[58:61], v[22:25], v[196:199], v[58:61]
	v_mfma_f32_16x16x32_bf16 v[10:13], v[10:13], v[200:203], v[34:37]
	v_mfma_f32_16x16x32_bf16 v[10:13], v[14:17], v[204:207], v[10:13]
	v_mfma_f32_16x16x32_bf16 v[14:17], v[18:21], v[200:203], v[30:33]
	v_mfma_f32_16x16x32_bf16 v[14:17], v[22:25], v[204:207], v[14:17]
	s_setprio 0
	s_setprio 1
	v_mfma_f32_16x16x32_bf16 v[30:33], v[26:29], v[184:187], v[70:73]
	v_mfma_f32_16x16x32_bf16 v[70:73], v[38:41], v[188:191], v[30:33]
	v_mfma_f32_16x16x32_bf16 v[30:33], v[50:53], v[184:187], v[66:69]
	v_mfma_f32_16x16x32_bf16 v[66:69], v[54:57], v[188:191], v[30:33]
	v_mfma_f32_16x16x32_bf16 v[30:33], v[26:29], v[192:195], v[46:49]
	v_mfma_f32_16x16x32_bf16 v[46:49], v[38:41], v[196:199], v[30:33]
	v_mfma_f32_16x16x32_bf16 v[30:33], v[50:53], v[192:195], v[42:45]
	v_mfma_f32_16x16x32_bf16 v[42:45], v[54:57], v[196:199], v[30:33]
	v_mfma_f32_16x16x32_bf16 v[6:9], v[26:29], v[200:203], v[6:9]
	v_mfma_f32_16x16x32_bf16 v[6:9], v[38:41], v[204:207], v[6:9]
	v_mfma_f32_16x16x32_bf16 v[2:5], v[50:53], v[200:203], v[2:5]
	v_mfma_f32_16x16x32_bf16 v[2:5], v[54:57], v[204:207], v[2:5]
	v_mfma_f32_16x16x32_bf16 v[18:21], v[26:29], v[172:175], v[86:89]
	v_mfma_f32_16x16x32_bf16 v[18:21], v[38:41], v[176:179], v[18:21]
	v_mfma_f32_16x16x32_bf16 v[22:25], v[50:53], v[172:175], v[82:85]
	v_mfma_f32_16x16x32_bf16 v[22:25], v[54:57], v[176:179], v[22:25]
	s_setprio 0
	s_barrier
; #define PG8_STAGE(bufoff, gbase, voff) do { _Pragma("unroll") for (int _i = 0; _i < 2; ++_i) \
;         __builtin_amdgcn_global_load_lds((const unsigned*)((const char*)(gbase) + (voff)[_i]), (PG8_LAS unsigned*)(lds + (bufoff) + ldsw + _i * 8192), 16, 0, 0); } while (0)
; #define PG8_LDA(dst, b, h) do { _Pragma("unroll") for (int m = 0; m < 4; ++m) _Pragma("unroll") for (int k = 0; k < 2; ++k) dst[m][k] = *(const PG8_LAS bf16x8*)(lds + PG8_SA(b, h) + aoff + m * 2048 + k * 1024); } while (0)
; #define PG8_LDB(dst, b, h) do { _Pragma("unroll") for (int n = 0; n < 2; ++n) _Pragma("unroll") for (int k = 0; k < 2; ++k) dst[n][k] = *(const PG8_LAS bf16x8*)(lds + PG8_SB(b, h) + boff + n * 2048 + k * 1024); } while (0)
; #define PG8_MMA(ai, bj, At, Bt) do { __builtin_amdgcn_s_setprio(1); _Pragma("unroll") for (int m = 0; m < 4; ++m) _Pragma("unroll") for (int n = 0; n < 2; ++n) _Pragma("unroll") for (int k = 0; k < 2; ++k) \
;         acc[ai][bj][m][n] = __builtin_amdgcn_mfma_f32_16x16x32_bf16(Bt[n][k], At[m][k], acc[ai][bj][m][n], 0, 0, 0); __builtin_amdgcn_s_setprio(0); } while (0)
; #define PG8_WAIT_V(n) asm volatile("s_waitcnt vmcnt(" #n ")" ::: "memory")
; #define PG8_WAIT_L(n) asm volatile("s_waitcnt lgkmcnt(" #n ")" ::: "memory")
; #define PG8_BAR __builtin_amdgcn_s_barrier()
; #define PG8_SCHED __builtin_amdgcn_sched_barrier(0)
;     ...
;             PG8_LDB(B0, 1, 0); PG8_LDB(B1, 1, 1); PG8_SCHED; PG8_LDA(At, 1, 0); PG8_STAGE(PG8_SA(0, 1), a2 + hstepA, voffA);
;             PG8_WAIT_V(8); PG8_WAIT_L(0); PG8_BAR; PG8_MMA(0, 0, At, B0); PG8_MMA(0, 1, At, B1); PG8_BAR; PG8_SCHED;
;             PG8_LDA(At, 1, 1); PG8_STAGE(PG8_SB(1, 0), b3, voffB); PG8_STAGE(PG8_SB(1, 1), b3 + hstepB, voffB); PG8_STAGE(PG8_SA(1, 0), a3, voffA);
;             PG8_WAIT_V(8); PG8_WAIT_L(0); PG8_BAR; PG8_MMA(1, 0, At, B0); PG8_MMA(1, 1, At, B1); PG8_BAR; PG8_SCHED;
	s_add_i32 s65, 0, 0x18000
	v_add_u32_e32 v34, s65, v182
	s_add_i32 s66, 0, 0x1c000
	ds_read_b128 v[26:29], v34
	ds_read_b128 v[30:33], v34 offset:1024
	ds_read_b128 v[38:41], v34 offset:2048
	ds_read_b128 v[50:53], v34 offset:3072
	v_add_u32_e32 v34, s66, v182
	ds_read_b128 v[54:57], v34
	ds_read_b128 v[172:175], v34 offset:1024
	ds_read_b128 v[176:179], v34 offset:2048
	ds_read_b128 v[184:187], v34 offset:3072
	s_add_u32 s90, s90, 0x4000
	s_addc_u32 s91, s91, 0
	s_mov_b32 m0, s14
	ds_read_b128 v[34:37], v183 offset:32768
	ds_read_b128 v[82:85], v183 offset:33792
	ds_read_b128 v[86:89], v183 offset:34816
	ds_read_b128 v[188:191], v183 offset:35840
	ds_read_b128 v[192:195], v183 offset:36864
	ds_read_b128 v[196:199], v183 offset:37888
	ds_read_b128 v[200:203], v183 offset:38912
	ds_read_b128 v[204:207], v183 offset:39936
	global_load_lds_dwordx4 v166, s[90:91]
	v_lshl_add_u64 v[208:209], s[90:91], 0, v[164:165]
	s_mov_b32 m0, s15
	s_nop 0
	global_load_lds_dwordx4 v[208:209], off
	s_waitcnt vmcnt(8)
	s_waitcnt lgkmcnt(0)
	s_barrier
	s_setprio 1
	s_waitcnt lgkmcnt(0)
	v_mfma_f32_16x16x32_bf16 v[158:161], v[26:29], v[34:37], v[158:161]
	v_mfma_f32_16x16x32_bf16 v[158:161], v[30:33], v[82:85], v[158:161]
	v_mfma_f32_16x16x32_bf16 v[154:157], v[50:53], v[82:85], v[154:157]
	v_mfma_f32_16x16x32_bf16 v[154:157], v[38:41], v[34:37], v[154:157]
	v_mfma_f32_16x16x32_bf16 v[138:141], v[38:41], v[86:89], v[138:141]
	v_mfma_f32_16x16x32_bf16 v[138:141], v[50:53], v[188:191], v[138:141]
	v_mfma_f32_16x16x32_bf16 v[142:145], v[30:33], v[188:191], v[142:145]
	v_mfma_f32_16x16x32_bf16 v[142:145], v[26:29], v[86:89], v[142:145]
	v_mfma_f32_16x16x32_bf16 v[126:129], v[26:29], v[192:195], v[126:129]
	v_mfma_f32_16x16x32_bf16 v[126:129], v[30:33], v[196:199], v[126:129]
	v_mfma_f32_16x16x32_bf16 v[122:125], v[50:53], v[196:199], v[122:125]
	v_mfma_f32_16x16x32_bf16 v[122:125], v[38:41], v[192:195], v[122:125]
	v_mfma_f32_16x16x32_bf16 v[106:109], v[38:41], v[200:203], v[106:109]
	v_mfma_f32_16x16x32_bf16 v[106:109], v[50:53], v[204:207], v[106:109]
	v_mfma_f32_16x16x32_bf16 v[110:113], v[30:33], v[204:207], v[110:113]
	v_mfma_f32_16x16x32_bf16 v[110:113], v[26:29], v[200:203], v[110:113]
	s_setprio 0
	s_setprio 1
	v_mfma_f32_16x16x32_bf16 v[150:153], v[54:57], v[34:37], v[150:153]
	v_mfma_f32_16x16x32_bf16 v[150:153], v[172:175], v[82:85], v[150:153]
	v_mfma_f32_16x16x32_bf16 v[34:37], v[176:179], v[34:37], v[146:149]
	v_mfma_f32_16x16x32_bf16 v[146:149], v[184:187], v[82:85], v[34:37]
	v_mfma_f32_16x16x32_bf16 v[34:37], v[54:57], v[86:89], v[134:137]
	v_mfma_f32_16x16x32_bf16 v[134:137], v[172:175], v[188:191], v[34:37]
	v_mfma_f32_16x16x32_bf16 v[34:37], v[176:179], v[86:89], v[130:133]
	v_mfma_f32_16x16x32_bf16 v[130:133], v[184:187], v[188:191], v[34:37]
	v_mfma_f32_16x16x32_bf16 v[34:37], v[54:57], v[192:195], v[118:121]
	v_mfma_f32_16x16x32_bf16 v[118:121], v[172:175], v[196:199], v[34:37]
	v_mfma_f32_16x16x32_bf16 v[34:37], v[176:179], v[192:195], v[114:117]
	v_mfma_f32_16x16x32_bf16 v[114:117], v[184:187], v[196:199], v[34:37]
	v_mfma_f32_16x16x32_bf16 v[34:37], v[54:57], v[200:203], v[102:105]
	v_mfma_f32_16x16x32_bf16 v[102:105], v[172:175], v[204:207], v[34:37]
	v_mfma_f32_16x16x32_bf16 v[34:37], v[176:179], v[200:203], v[98:101]
	v_mfma_f32_16x16x32_bf16 v[98:101], v[184:187], v[204:207], v[34:37]
	s_setprio 0
	s_barrier
	s_add_u32 s90, s88, 0x8000
	s_addc_u32 s91, s89, 0
	s_add_i32 s65, s65, s2
	s_nop 0
	s_mov_b32 m0, s65
	ds_read_b128 v[82:85], v183 offset:49152
	ds_read_b128 v[188:191], v183 offset:50176
	ds_read_b128 v[192:195], v183 offset:51200
	ds_read_b128 v[196:199], v183 offset:52224
	ds_read_b128 v[200:203], v183 offset:53248
	ds_read_b128 v[204:207], v183 offset:54272
	ds_read_b128 v[208:211], v183 offset:55296
	ds_read_b128 v[216:219], v183 offset:56320
	global_load_lds_dwordx4 v0, s[90:91]
	s_add_i32 m0, s65, 0x2000
	s_add_u32 s88, s88, 0xc000
	s_addc_u32 s89, s89, 0
	s_add_i32 s65, s66, s2
	global_load_lds_dwordx4 v162, s[90:91]
	s_mov_b32 m0, s65
	s_nop 0
	global_load_lds_dwordx4 v0, s[88:89]
	s_add_i32 m0, s65, 0x2000
	s_nop 0
	global_load_lds_dwordx4 v162, s[88:89]
	s_mov_b32 m0, s71
	s_nop 0
	global_load_lds_dwordx4 v166, s[86:87]
	v_lshl_add_u64 v[34:35], s[86:87], 0, v[164:165]
	s_mov_b32 m0, s80
	s_nop 0
	global_load_lds_dwordx4 v[34:35], off
	s_waitcnt vmcnt(8)
	s_waitcnt lgkmcnt(0)
	s_barrier
	s_setprio 1
	s_waitcnt lgkmcnt(0)
	v_mfma_f32_16x16x32_bf16 v[34:37], v[26:29], v[82:85], v[94:97]
	v_mfma_f32_16x16x32_bf16 v[94:97], v[30:33], v[188:191], v[34:37]
	v_mfma_f32_16x16x32_bf16 v[34:37], v[38:41], v[82:85], v[90:93]
	v_mfma_f32_16x16x32_bf16 v[90:93], v[50:53], v[188:191], v[34:37]
	v_mfma_f32_16x16x32_bf16 v[34:37], v[26:29], v[192:195], v[78:81]
	v_mfma_f32_16x16x32_bf16 v[78:81], v[30:33], v[196:199], v[34:37]
	v_mfma_f32_16x16x32_bf16 v[34:37], v[38:41], v[192:195], v[74:77]
	v_mfma_f32_16x16x32_bf16 v[74:77], v[50:53], v[196:199], v[34:37]
	v_mfma_f32_16x16x32_bf16 v[34:37], v[26:29], v[200:203], v[62:65]
	v_mfma_f32_16x16x32_bf16 v[62:65], v[30:33], v[204:207], v[34:37]
	v_mfma_f32_16x16x32_bf16 v[34:37], v[38:41], v[200:203], v[58:61]
	v_mfma_f32_16x16x32_bf16 v[58:61], v[50:53], v[204:207], v[34:37]
	v_mfma_f32_16x16x32_bf16 v[10:13], v[26:29], v[208:211], v[10:13]
	v_mfma_f32_16x16x32_bf16 v[34:37], v[30:33], v[216:219], v[10:13]
	v_mfma_f32_16x16x32_bf16 v[10:13], v[38:41], v[208:211], v[14:17]
	v_mfma_f32_16x16x32_bf16 v[30:33], v[50:53], v[216:219], v[10:13]
	s_setprio 0
	s_setprio 1
	v_mfma_f32_16x16x32_bf16 v[10:13], v[54:57], v[82:85], v[18:21]
	v_mfma_f32_16x16x32_bf16 v[86:89], v[172:175], v[188:191], v[10:13]
	v_mfma_f32_16x16x32_bf16 v[10:13], v[176:179], v[82:85], v[22:25]
	v_mfma_f32_16x16x32_bf16 v[82:85], v[184:187], v[188:191], v[10:13]
	v_mfma_f32_16x16x32_bf16 v[10:13], v[54:57], v[192:195], v[70:73]
	v_mfma_f32_16x16x32_bf16 v[70:73], v[172:175], v[196:199], v[10:13]
	v_mfma_f32_16x16x32_bf16 v[10:13], v[176:179], v[192:195], v[66:69]
	v_mfma_f32_16x16x32_bf16 v[66:69], v[184:187], v[196:199], v[10:13]
	v_mfma_f32_16x16x32_bf16 v[10:13], v[54:57], v[200:203], v[46:49]
	v_mfma_f32_16x16x32_bf16 v[46:49], v[172:175], v[204:207], v[10:13]
	v_mfma_f32_16x16x32_bf16 v[10:13], v[176:179], v[200:203], v[42:45]
	v_mfma_f32_16x16x32_bf16 v[42:45], v[184:187], v[204:207], v[10:13]
	v_mfma_f32_16x16x32_bf16 v[6:9], v[54:57], v[208:211], v[6:9]
	v_mfma_f32_16x16x32_bf16 v[6:9], v[172:175], v[216:219], v[6:9]
	v_mfma_f32_16x16x32_bf16 v[2:5], v[176:179], v[208:211], v[2:5]
	v_mfma_f32_16x16x32_bf16 v[2:5], v[184:187], v[216:219], v[2:5]
	s_setprio 0
	s_barrier
	s_add_i32 vcc_lo, vcc_lo, 2
	s_add_u32 s6, s6, 0x10000
	s_addc_u32 s7, s7, 0
	s_add_u32 s56, s56, 0x10000
	s_addc_u32 s57, s57, 0
	s_cmp_gt_u32 vcc_lo, 29
	s_cbranch_scc0 .LBB0_328
	s_and_b64 vcc, exec, s[26:27]
	s_cbranch_vccz .LBB0_331
	s_barrier

; #define PG8_STAGE(bufoff, gbase, voff) do { _Pragma("unroll") for (int _i = 0; _i < 2; ++_i) \
;         __builtin_amdgcn_global_load_lds((const unsigned*)((const char*)(gbase) + (voff)[_i]), (PG8_LAS unsigned*)(lds + (bufoff) + ldsw + _i * 8192), 16, 0, 0); } while (0)
; #define PG8_LDA(dst, b, h) do { _Pragma("unroll") for (int m = 0; m < 4; ++m) _Pragma("unroll") for (int k = 0; k < 2; ++k) dst[m][k] = *(const PG8_LAS bf16x8*)(lds + PG8_SA(b, h) + aoff + m * 2048 + k * 1024); } while (0)
; #define PG8_LDB(dst, b, h) do { _Pragma("unroll") for (int n = 0; n < 2; ++n) _Pragma("unroll") for (int k = 0; k < 2; ++k) dst[n][k] = *(const PG8_LAS bf16x8*)(lds + PG8_SB(b, h) + boff + n * 2048 + k * 1024); } while (0)
; #define PG8_MMA(ai, bj, At, Bt) do { __builtin_amdgcn_s_setprio(1); _Pragma("unroll") for (int m = 0; m < 4; ++m) _Pragma("unroll") for (int n = 0; n < 2; ++n) _Pragma("unroll") for (int k = 0; k < 2; ++k) \
;         acc[ai][bj][m][n] = __builtin_amdgcn_mfma_f32_16x16x32_bf16(Bt[n][k], At[m][k], acc[ai][bj][m][n], 0, 0, 0); __builtin_amdgcn_s_setprio(0); } while (0)
; #define PG8_WAIT_V(n) asm volatile("s_waitcnt vmcnt(" #n ")" ::: "memory")
; #define PG8_WAIT_L(n) asm volatile("s_waitcnt lgkmcnt(" #n ")" ::: "memory")
; #define PG8_BAR __builtin_amdgcn_s_barrier()
; #define PG8_SCHED __builtin_amdgcn_sched_barrier(0)
;     ...
;         for (int t = 0; t < nt; t += 2) {
;             const bool last = (t == nt - 2);
;             const char* a1 = cA + (ptrdiff_t)(t + 1) * kstepA;
;             const char* a2 = last ? nA : cA + (ptrdiff_t)(t + 2) * kstepA; const char* b2 = last ? nB : cB + (ptrdiff_t)(t + 2) * kstep;
;             const char* a3 = a2 + kstepA; const char* b3 = b2 + kstep;
;             if (last && has_next) S.a_ready(nxt);
;             if constexpr (SP2) {
;             PG8_LDB(B0, 0, 0); PG8_LDB(B1, 0, 1); PG8_SCHED; PG8_LDA(At, 0, 0); PG8_STAGE(PG8_SA(1, 1), a1 + hstepA, voffA);
;             PG8_WAIT_V(8); PG8_WAIT_L(0); PG8_BAR; PG8_MMA(0, 0, At, B0); PG8_MMA(0, 1, At, B1); PG8_BAR; PG8_SCHED;
;             PG8_LDA(At, 0, 1); PG8_STAGE(PG8_SB(0, 0), b2, voffB); PG8_STAGE(PG8_SB(0, 1), b2 + hstepB, voffB); PG8_STAGE(PG8_SA(0, 0), a2, voffA);
;             PG8_WAIT_V(8); PG8_WAIT_L(0); PG8_BAR; PG8_MMA(1, 0, At, B0); PG8_MMA(1, 1, At, B1); PG8_BAR; PG8_SCHED;
.LBB0_1128:
	s_add_u32 s36, s34, 0x4000
	s_addc_u32 s37, s35, 0
	s_cmp_eq_u32 s57, 28
	s_cselect_b32 s86, s29, s36
	s_cselect_b32 s87, s23, s37
	s_cselect_b32 s46, s31, s44
	s_cselect_b32 s47, s21, s56
	s_add_u32 s36, s86, 0x8000
	s_addc_u32 s37, s87, 0
	s_add_i32 s65, 0, 0x10000
	v_add_u32_e32 v0, s65, v242
	s_add_i32 s66, 0, 0x14000
	s_waitcnt lgkmcnt(0)
	ds_read_b128 v[130:133], v0
	ds_read_b128 v[134:137], v0 offset:1024
	ds_read_b128 v[138:141], v0 offset:2048
	ds_read_b128 v[142:145], v0 offset:3072
	v_add_u32_e32 v0, s66, v242
	ds_read_b128 v[146:149], v0
	ds_read_b128 v[150:153], v0 offset:1024
	ds_read_b128 v[154:157], v0 offset:2048
	ds_read_b128 v[158:161], v0 offset:3072
	s_add_i32 m0, s51, 0xc000
	ds_read_b128 v[162:165], v243
	ds_read_b128 v[166:169], v243 offset:1024
	ds_read_b128 v[170:173], v243 offset:2048
	ds_read_b128 v[174:177], v243 offset:3072
	ds_read_b128 v[178:181], v243 offset:4096
	ds_read_b128 v[182:185], v243 offset:5120
	ds_read_b128 v[198:201], v243 offset:6144
	ds_read_b128 v[202:205], v243 offset:7168
	global_load_lds_dwordx4 v194, s[34:35]
	s_add_i32 m0, s51, 0xe000
	s_nop 0
	global_load_lds_dwordx4 v196, s[34:35]
	s_waitcnt vmcnt(8)
	s_waitcnt lgkmcnt(0)
	s_barrier
	s_setprio 1
	s_waitcnt lgkmcnt(0)
	v_mfma_f32_16x16x32_bf16 v[126:129], v[130:133], v[162:165], v[126:129]
	v_mfma_f32_16x16x32_bf16 v[126:129], v[134:137], v[166:169], v[126:129]
	v_mfma_f32_16x16x32_bf16 v[122:125], v[142:145], v[166:169], v[122:125]
	v_mfma_f32_16x16x32_bf16 v[122:125], v[138:141], v[162:165], v[122:125]
	v_mfma_f32_16x16x32_bf16 v[106:109], v[138:141], v[170:173], v[106:109]
	v_mfma_f32_16x16x32_bf16 v[106:109], v[142:145], v[174:177], v[106:109]
	v_mfma_f32_16x16x32_bf16 v[110:113], v[134:137], v[174:177], v[110:113]
	v_mfma_f32_16x16x32_bf16 v[110:113], v[130:133], v[170:173], v[110:113]
	v_mfma_f32_16x16x32_bf16 v[94:97], v[130:133], v[178:181], v[94:97]
	v_mfma_f32_16x16x32_bf16 v[94:97], v[134:137], v[182:185], v[94:97]
	v_mfma_f32_16x16x32_bf16 v[90:93], v[142:145], v[182:185], v[90:93]
	v_mfma_f32_16x16x32_bf16 v[90:93], v[138:141], v[178:181], v[90:93]
	v_mfma_f32_16x16x32_bf16 v[74:77], v[138:141], v[198:201], v[74:77]
	v_mfma_f32_16x16x32_bf16 v[74:77], v[142:145], v[202:205], v[74:77]
	v_mfma_f32_16x16x32_bf16 v[78:81], v[134:137], v[202:205], v[78:81]
	v_mfma_f32_16x16x32_bf16 v[78:81], v[130:133], v[198:201], v[78:81]
	s_setprio 0
	s_setprio 1
	v_mfma_f32_16x16x32_bf16 v[118:121], v[146:149], v[162:165], v[118:121]
	v_mfma_f32_16x16x32_bf16 v[118:121], v[150:153], v[166:169], v[118:121]
	v_mfma_f32_16x16x32_bf16 v[114:117], v[158:161], v[166:169], v[114:117]
	v_mfma_f32_16x16x32_bf16 v[114:117], v[154:157], v[162:165], v[114:117]
	v_mfma_f32_16x16x32_bf16 v[98:101], v[154:157], v[170:173], v[98:101]
	v_mfma_f32_16x16x32_bf16 v[98:101], v[158:161], v[174:177], v[98:101]
	v_mfma_f32_16x16x32_bf16 v[102:105], v[150:153], v[174:177], v[102:105]
	v_mfma_f32_16x16x32_bf16 v[102:105], v[146:149], v[170:173], v[102:105]
	v_mfma_f32_16x16x32_bf16 v[86:89], v[146:149], v[178:181], v[86:89]
	v_mfma_f32_16x16x32_bf16 v[86:89], v[150:153], v[182:185], v[86:89]
	v_mfma_f32_16x16x32_bf16 v[82:85], v[158:161], v[182:185], v[82:85]
	v_mfma_f32_16x16x32_bf16 v[82:85], v[154:157], v[178:181], v[82:85]
	v_mfma_f32_16x16x32_bf16 v[66:69], v[154:157], v[198:201], v[66:69]
	v_mfma_f32_16x16x32_bf16 v[66:69], v[158:161], v[202:205], v[66:69]
	v_mfma_f32_16x16x32_bf16 v[70:73], v[150:153], v[202:205], v[70:73]
	v_mfma_f32_16x16x32_bf16 v[70:73], v[146:149], v[198:201], v[70:73]
	s_setprio 0
	s_barrier
	s_add_i32 s65, s65, s49
	s_mov_b32 m0, s65
	ds_read_b128 v[162:165], v243 offset:16384
	ds_read_b128 v[166:169], v243 offset:17408
	ds_read_b128 v[170:173], v243 offset:18432
	ds_read_b128 v[174:177], v243 offset:19456
	ds_read_b128 v[178:181], v243 offset:20480
	ds_read_b128 v[182:185], v243 offset:21504
	ds_read_b128 v[198:201], v243 offset:22528
	ds_read_b128 v[202:205], v243 offset:23552
	global_load_lds_dwordx4 v188, s[46:47]
	s_add_i32 m0, s65, 0x2000
	s_add_u32 s90, s46, 0x4000
	s_addc_u32 s91, s47, 0
	s_add_i32 s65, s66, s49
	global_load_lds_dwordx4 v192, s[46:47]
	s_mov_b32 m0, s65
	s_nop 0
	global_load_lds_dwordx4 v188, s[90:91]
	s_add_i32 m0, s65, 0x2000
	s_nop 0
	global_load_lds_dwordx4 v192, s[90:91]
	s_mov_b32 m0, s51
	s_nop 0
	global_load_lds_dwordx4 v186, s[86:87]
	s_mov_b32 m0, s54
	s_nop 0
	global_load_lds_dwordx4 v190, s[86:87]
	s_waitcnt vmcnt(8)
	s_waitcnt lgkmcnt(0)
	s_barrier
	s_setprio 1
	s_waitcnt lgkmcnt(0)
	v_mfma_f32_16x16x32_bf16 v[62:65], v[130:133], v[162:165], v[62:65]
	v_mfma_f32_16x16x32_bf16 v[62:65], v[134:137], v[166:169], v[62:65]
	v_mfma_f32_16x16x32_bf16 v[58:61], v[142:145], v[166:169], v[58:61]
	v_mfma_f32_16x16x32_bf16 v[58:61], v[138:141], v[162:165], v[58:61]
	v_mfma_f32_16x16x32_bf16 v[42:45], v[138:141], v[170:173], v[42:45]
	v_mfma_f32_16x16x32_bf16 v[42:45], v[142:145], v[174:177], v[42:45]
	v_mfma_f32_16x16x32_bf16 v[46:49], v[134:137], v[174:177], v[46:49]
	v_mfma_f32_16x16x32_bf16 v[46:49], v[130:133], v[170:173], v[46:49]
	v_mfma_f32_16x16x32_bf16 v[30:33], v[130:133], v[178:181], v[30:33]
	v_mfma_f32_16x16x32_bf16 v[30:33], v[134:137], v[182:185], v[30:33]
	v_mfma_f32_16x16x32_bf16 v[26:29], v[142:145], v[182:185], v[26:29]
	v_mfma_f32_16x16x32_bf16 v[26:29], v[138:141], v[178:181], v[26:29]
	v_mfma_f32_16x16x32_bf16 v[10:13], v[138:141], v[198:201], v[10:13]
	v_mfma_f32_16x16x32_bf16 v[10:13], v[142:145], v[202:205], v[10:13]
	v_mfma_f32_16x16x32_bf16 v[14:17], v[134:137], v[202:205], v[14:17]
	v_mfma_f32_16x16x32_bf16 v[14:17], v[130:133], v[198:201], v[14:17]
	s_setprio 0
	s_setprio 1
	v_mfma_f32_16x16x32_bf16 v[54:57], v[146:149], v[162:165], v[54:57]
	v_mfma_f32_16x16x32_bf16 v[54:57], v[150:153], v[166:169], v[54:57]
	v_mfma_f32_16x16x32_bf16 v[50:53], v[158:161], v[166:169], v[50:53]
	v_mfma_f32_16x16x32_bf16 v[50:53], v[154:157], v[162:165], v[50:53]
	v_mfma_f32_16x16x32_bf16 v[34:37], v[154:157], v[170:173], v[34:37]
	v_mfma_f32_16x16x32_bf16 v[34:37], v[158:161], v[174:177], v[34:37]
	v_mfma_f32_16x16x32_bf16 v[38:41], v[150:153], v[174:177], v[38:41]
	v_mfma_f32_16x16x32_bf16 v[38:41], v[146:149], v[170:173], v[38:41]
	v_mfma_f32_16x16x32_bf16 v[22:25], v[146:149], v[178:181], v[22:25]
	v_mfma_f32_16x16x32_bf16 v[22:25], v[150:153], v[182:185], v[22:25]
	v_mfma_f32_16x16x32_bf16 v[18:21], v[158:161], v[182:185], v[18:21]
	v_mfma_f32_16x16x32_bf16 v[18:21], v[154:157], v[178:181], v[18:21]
	v_mfma_f32_16x16x32_bf16 v[2:5], v[154:157], v[198:201], v[2:5]
	v_mfma_f32_16x16x32_bf16 v[2:5], v[158:161], v[202:205], v[2:5]
	v_mfma_f32_16x16x32_bf16 v[6:9], v[150:153], v[202:205], v[6:9]
	v_mfma_f32_16x16x32_bf16 v[6:9], v[146:149], v[198:201], v[6:9]
	s_setprio 0
	s_barrier
; #define PG8_STAGE(bufoff, gbase, voff) do { _Pragma("unroll") for (int _i = 0; _i < 2; ++_i) \
;         __builtin_amdgcn_global_load_lds((const unsigned*)((const char*)(gbase) + (voff)[_i]), (PG8_LAS unsigned*)(lds + (bufoff) + ldsw + _i * 8192), 16, 0, 0); } while (0)
; #define PG8_LDA(dst, b, h) do { _Pragma("unroll") for (int m = 0; m < 4; ++m) _Pragma("unroll") for (int k = 0; k < 2; ++k) dst[m][k] = *(const PG8_LAS bf16x8*)(lds + PG8_SA(b, h) + aoff + m * 2048 + k * 1024); } while (0)
; #define PG8_LDB(dst, b, h) do { _Pragma("unroll") for (int n = 0; n < 2; ++n) _Pragma("unroll") for (int k = 0; k < 2; ++k) dst[n][k] = *(const PG8_LAS bf16x8*)(lds + PG8_SB(b, h) + boff + n * 2048 + k * 1024); } while (0)
; #define PG8_MMA(ai, bj, At, Bt) do { __builtin_amdgcn_s_setprio(1); _Pragma("unroll") for (int m = 0; m < 4; ++m) _Pragma("unroll") for (int n = 0; n < 2; ++n) _Pragma("unroll") for (int k = 0; k < 2; ++k) \
;         acc[ai][bj][m][n] = __builtin_amdgcn_mfma_f32_16x16x32_bf16(Bt[n][k], At[m][k], acc[ai][bj][m][n], 0, 0, 0); __builtin_amdgcn_s_setprio(0); } while (0)
; #define PG8_WAIT_V(n) asm volatile("s_waitcnt vmcnt(" #n ")" ::: "memory")
; #define PG8_WAIT_L(n) asm volatile("s_waitcnt lgkmcnt(" #n ")" ::: "memory")
; #define PG8_BAR __builtin_amdgcn_s_barrier()
; #define PG8_SCHED __builtin_amdgcn_sched_barrier(0)
;     ...
;             PG8_LDB(B0, 1, 0); PG8_LDB(B1, 1, 1); PG8_SCHED; PG8_LDA(At, 1, 0); PG8_STAGE(PG8_SA(0, 1), a2 + hstepA, voffA);
;             PG8_WAIT_V(8); PG8_WAIT_L(0); PG8_BAR; PG8_MMA(0, 0, At, B0); PG8_MMA(0, 1, At, B1); PG8_BAR; PG8_SCHED;
;             PG8_LDA(At, 1, 1); PG8_STAGE(PG8_SB(1, 0), b3, voffB); PG8_STAGE(PG8_SB(1, 1), b3 + hstepB, voffB); PG8_STAGE(PG8_SA(1, 0), a3, voffA);
;             PG8_WAIT_V(8); PG8_WAIT_L(0); PG8_BAR; PG8_MMA(1, 0, At, B0); PG8_MMA(1, 1, At, B1); PG8_BAR; PG8_SCHED;
	s_add_i32 s65, 0, 0x18000
	v_add_u32_e32 v0, s65, v242
	s_add_i32 s66, 0, 0x1c000
	ds_read_b128 v[130:133], v0
	ds_read_b128 v[134:137], v0 offset:1024
	ds_read_b128 v[138:141], v0 offset:2048
	ds_read_b128 v[142:145], v0 offset:3072
	v_add_u32_e32 v0, s66, v242
	ds_read_b128 v[146:149], v0
	ds_read_b128 v[150:153], v0 offset:1024
	ds_read_b128 v[154:157], v0 offset:2048
	ds_read_b128 v[158:161], v0 offset:3072
	s_add_u32 s86, s86, 0x4000
	s_addc_u32 s87, s87, 0
	s_mov_b32 m0, s55
	ds_read_b128 v[162:165], v243 offset:32768
	ds_read_b128 v[166:169], v243 offset:33792
	ds_read_b128 v[170:173], v243 offset:34816
	ds_read_b128 v[174:177], v243 offset:35840
	ds_read_b128 v[178:181], v243 offset:36864
	ds_read_b128 v[182:185], v243 offset:37888
	ds_read_b128 v[198:201], v243 offset:38912
	ds_read_b128 v[202:205], v243 offset:39936
	global_load_lds_dwordx4 v186, s[86:87]
	s_mov_b32 m0, s61
	s_nop 0
	global_load_lds_dwordx4 v190, s[86:87]
	s_waitcnt vmcnt(8)
	s_waitcnt lgkmcnt(0)
	s_barrier
	s_setprio 1
	s_waitcnt lgkmcnt(0)
	v_mfma_f32_16x16x32_bf16 v[126:129], v[130:133], v[162:165], v[126:129]
	v_mfma_f32_16x16x32_bf16 v[126:129], v[134:137], v[166:169], v[126:129]
	v_mfma_f32_16x16x32_bf16 v[122:125], v[142:145], v[166:169], v[122:125]
	v_mfma_f32_16x16x32_bf16 v[122:125], v[138:141], v[162:165], v[122:125]
	v_mfma_f32_16x16x32_bf16 v[106:109], v[138:141], v[170:173], v[106:109]
	v_mfma_f32_16x16x32_bf16 v[106:109], v[142:145], v[174:177], v[106:109]
	v_mfma_f32_16x16x32_bf16 v[110:113], v[134:137], v[174:177], v[110:113]
	v_mfma_f32_16x16x32_bf16 v[110:113], v[130:133], v[170:173], v[110:113]
	v_mfma_f32_16x16x32_bf16 v[94:97], v[130:133], v[178:181], v[94:97]
	v_mfma_f32_16x16x32_bf16 v[94:97], v[134:137], v[182:185], v[94:97]
	v_mfma_f32_16x16x32_bf16 v[90:93], v[142:145], v[182:185], v[90:93]
	v_mfma_f32_16x16x32_bf16 v[90:93], v[138:141], v[178:181], v[90:93]
	v_mfma_f32_16x16x32_bf16 v[74:77], v[138:141], v[198:201], v[74:77]
	v_mfma_f32_16x16x32_bf16 v[74:77], v[142:145], v[202:205], v[74:77]
	v_mfma_f32_16x16x32_bf16 v[78:81], v[134:137], v[202:205], v[78:81]
	v_mfma_f32_16x16x32_bf16 v[78:81], v[130:133], v[198:201], v[78:81]
	s_setprio 0
	s_setprio 1
	v_mfma_f32_16x16x32_bf16 v[118:121], v[146:149], v[162:165], v[118:121]
	v_mfma_f32_16x16x32_bf16 v[118:121], v[150:153], v[166:169], v[118:121]
	v_mfma_f32_16x16x32_bf16 v[114:117], v[158:161], v[166:169], v[114:117]
	v_mfma_f32_16x16x32_bf16 v[114:117], v[154:157], v[162:165], v[114:117]
	v_mfma_f32_16x16x32_bf16 v[98:101], v[154:157], v[170:173], v[98:101]
	v_mfma_f32_16x16x32_bf16 v[98:101], v[158:161], v[174:177], v[98:101]
	v_mfma_f32_16x16x32_bf16 v[102:105], v[150:153], v[174:177], v[102:105]
	v_mfma_f32_16x16x32_bf16 v[102:105], v[146:149], v[170:173], v[102:105]
	v_mfma_f32_16x16x32_bf16 v[86:89], v[146:149], v[178:181], v[86:89]
	v_mfma_f32_16x16x32_bf16 v[86:89], v[150:153], v[182:185], v[86:89]
	v_mfma_f32_16x16x32_bf16 v[82:85], v[158:161], v[182:185], v[82:85]
	v_mfma_f32_16x16x32_bf16 v[82:85], v[154:157], v[178:181], v[82:85]
	v_mfma_f32_16x16x32_bf16 v[66:69], v[154:157], v[198:201], v[66:69]
	v_mfma_f32_16x16x32_bf16 v[66:69], v[158:161], v[202:205], v[66:69]
	v_mfma_f32_16x16x32_bf16 v[70:73], v[150:153], v[202:205], v[70:73]
	v_mfma_f32_16x16x32_bf16 v[70:73], v[146:149], v[198:201], v[70:73]
	s_setprio 0
	s_barrier
	s_add_u32 s86, s46, 0x8000
	s_addc_u32 s87, s47, 0
	s_add_i32 s65, s65, s49
	s_mov_b32 m0, s65
	ds_read_b128 v[162:165], v243 offset:49152
	ds_read_b128 v[166:169], v243 offset:50176
	ds_read_b128 v[170:173], v243 offset:51200
	ds_read_b128 v[174:177], v243 offset:52224
	ds_read_b128 v[178:181], v243 offset:53248
	ds_read_b128 v[182:185], v243 offset:54272
	ds_read_b128 v[198:201], v243 offset:55296
	ds_read_b128 v[202:205], v243 offset:56320
	global_load_lds_dwordx4 v188, s[86:87]
	s_add_i32 m0, s65, 0x2000
	s_add_u32 s46, s46, 0xc000
	s_addc_u32 s47, s47, 0
	s_add_i32 s65, s66, s49
	global_load_lds_dwordx4 v192, s[86:87]
	s_mov_b32 m0, s65
	s_nop 0
	global_load_lds_dwordx4 v188, s[46:47]
	s_add_i32 m0, s65, 0x2000
	s_nop 0
	global_load_lds_dwordx4 v192, s[46:47]
	s_mov_b32 m0, s83
	s_nop 0
	global_load_lds_dwordx4 v186, s[36:37]
	v_lshl_add_u64 v[206:207], s[36:37], 0, v[190:191]
	s_mov_b32 m0, s85
	s_nop 0
	global_load_lds_dwordx4 v[206:207], off
	s_waitcnt vmcnt(8)
	s_waitcnt lgkmcnt(0)
	s_barrier
	s_setprio 1
	s_waitcnt lgkmcnt(0)
	v_mfma_f32_16x16x32_bf16 v[62:65], v[130:133], v[162:165], v[62:65]
	v_mfma_f32_16x16x32_bf16 v[62:65], v[134:137], v[166:169], v[62:65]
	v_mfma_f32_16x16x32_bf16 v[58:61], v[142:145], v[166:169], v[58:61]
	v_mfma_f32_16x16x32_bf16 v[58:61], v[138:141], v[162:165], v[58:61]
	v_mfma_f32_16x16x32_bf16 v[42:45], v[138:141], v[170:173], v[42:45]
	v_mfma_f32_16x16x32_bf16 v[42:45], v[142:145], v[174:177], v[42:45]
	v_mfma_f32_16x16x32_bf16 v[46:49], v[134:137], v[174:177], v[46:49]
	v_mfma_f32_16x16x32_bf16 v[46:49], v[130:133], v[170:173], v[46:49]
	v_mfma_f32_16x16x32_bf16 v[30:33], v[130:133], v[178:181], v[30:33]
	v_mfma_f32_16x16x32_bf16 v[30:33], v[134:137], v[182:185], v[30:33]
	v_mfma_f32_16x16x32_bf16 v[26:29], v[142:145], v[182:185], v[26:29]
	v_mfma_f32_16x16x32_bf16 v[26:29], v[138:141], v[178:181], v[26:29]
	v_mfma_f32_16x16x32_bf16 v[10:13], v[138:141], v[198:201], v[10:13]
	v_mfma_f32_16x16x32_bf16 v[10:13], v[142:145], v[202:205], v[10:13]
	v_mfma_f32_16x16x32_bf16 v[14:17], v[134:137], v[202:205], v[14:17]
	v_mfma_f32_16x16x32_bf16 v[14:17], v[130:133], v[198:201], v[14:17]
	s_setprio 0
	s_setprio 1
	v_mfma_f32_16x16x32_bf16 v[54:57], v[146:149], v[162:165], v[54:57]
	v_mfma_f32_16x16x32_bf16 v[54:57], v[150:153], v[166:169], v[54:57]
	v_mfma_f32_16x16x32_bf16 v[50:53], v[158:161], v[166:169], v[50:53]
	v_mfma_f32_16x16x32_bf16 v[50:53], v[154:157], v[162:165], v[50:53]
	v_mfma_f32_16x16x32_bf16 v[34:37], v[154:157], v[170:173], v[34:37]
	v_mfma_f32_16x16x32_bf16 v[34:37], v[158:161], v[174:177], v[34:37]
	v_mfma_f32_16x16x32_bf16 v[38:41], v[150:153], v[174:177], v[38:41]
	v_mfma_f32_16x16x32_bf16 v[38:41], v[146:149], v[170:173], v[38:41]
	v_mfma_f32_16x16x32_bf16 v[22:25], v[146:149], v[178:181], v[22:25]
	v_mfma_f32_16x16x32_bf16 v[22:25], v[150:153], v[182:185], v[22:25]
	v_mfma_f32_16x16x32_bf16 v[18:21], v[158:161], v[182:185], v[18:21]
	v_mfma_f32_16x16x32_bf16 v[18:21], v[154:157], v[178:181], v[18:21]
	v_mfma_f32_16x16x32_bf16 v[2:5], v[154:157], v[198:201], v[2:5]
	v_mfma_f32_16x16x32_bf16 v[2:5], v[158:161], v[202:205], v[2:5]
	v_mfma_f32_16x16x32_bf16 v[6:9], v[150:153], v[202:205], v[6:9]
	v_mfma_f32_16x16x32_bf16 v[6:9], v[146:149], v[198:201], v[6:9]
	s_setprio 0
	s_barrier
	s_add_i32 s57, s57, 2
	s_add_u32 s34, s34, 0x10000
	s_addc_u32 s35, s35, 0
	s_add_u32 s44, s44, 0x10000
	s_addc_u32 s56, s56, 0
	s_cmp_gt_u32 s57, 29
	s_cbranch_scc0 .LBB0_1128
	s_and_b64 vcc, exec, s[92:93]
	s_cbranch_vccz .LBB0_1131
	s_barrier

; #define PG8_STAGE(bufoff, gbase, voff) do { _Pragma("unroll") for (int _i = 0; _i < 2; ++_i) \
;         __builtin_amdgcn_global_load_lds((const unsigned*)((const char*)(gbase) + (voff)[_i]), (PG8_LAS unsigned*)(lds + (bufoff) + ldsw + _i * 8192), 16, 0, 0); } while (0)
; #define PG8_LDA(dst, b, h) do { _Pragma("unroll") for (int m = 0; m < 4; ++m) _Pragma("unroll") for (int k = 0; k < 2; ++k) dst[m][k] = *(const PG8_LAS bf16x8*)(lds + PG8_SA(b, h) + aoff + m * 2048 + k * 1024); } while (0)
; #define PG8_LDB(dst, b, h) do { _Pragma("unroll") for (int n = 0; n < 2; ++n) _Pragma("unroll") for (int k = 0; k < 2; ++k) dst[n][k] = *(const PG8_LAS bf16x8*)(lds + PG8_SB(b, h) + boff + n * 2048 + k * 1024); } while (0)
; #define PG8_MMA(ai, bj, At, Bt) do { __builtin_amdgcn_s_setprio(1); _Pragma("unroll") for (int m = 0; m < 4; ++m) _Pragma("unroll") for (int n = 0; n < 2; ++n) _Pragma("unroll") for (int k = 0; k < 2; ++k) \
;         acc[ai][bj][m][n] = __builtin_amdgcn_mfma_f32_16x16x32_bf16(Bt[n][k], At[m][k], acc[ai][bj][m][n], 0, 0, 0); __builtin_amdgcn_s_setprio(0); } while (0)
; #define PG8_WAIT_V(n) asm volatile("s_waitcnt vmcnt(" #n ")" ::: "memory")
; #define PG8_WAIT_L(n) asm volatile("s_waitcnt lgkmcnt(" #n ")" ::: "memory")
; #define PG8_BAR __builtin_amdgcn_s_barrier()
; #define PG8_SCHED __builtin_amdgcn_sched_barrier(0)
;     ...
;         for (int t = 0; t < nt; t += 2) {
;             const bool last = (t == nt - 2);
;             const char* a1 = cA + (ptrdiff_t)(t + 1) * kstepA;
;             const char* a2 = last ? nA : cA + (ptrdiff_t)(t + 2) * kstepA; const char* b2 = last ? nB : cB + (ptrdiff_t)(t + 2) * kstep;
;             const char* a3 = a2 + kstepA; const char* b3 = b2 + kstep;
;             if (last && has_next) S.a_ready(nxt);
;             if constexpr (SP2) {
;             PG8_LDB(B0, 0, 0); PG8_LDB(B1, 0, 1); PG8_SCHED; PG8_LDA(At, 0, 0); PG8_STAGE(PG8_SA(1, 1), a1 + hstepA, voffA);
;             PG8_WAIT_V(8); PG8_WAIT_L(0); PG8_BAR; PG8_MMA(0, 0, At, B0); PG8_MMA(0, 1, At, B1); PG8_BAR; PG8_SCHED;
;             PG8_LDA(At, 0, 1); PG8_STAGE(PG8_SB(0, 0), b2, voffB); PG8_STAGE(PG8_SB(0, 1), b2 + hstepB, voffB); PG8_STAGE(PG8_SA(0, 0), a2, voffA);
.LBB0_1256:
	s_add_u32 s36, s34, 0x10000
	s_addc_u32 s37, s35, 0
	s_cmp_eq_u32 s66, 28
	s_cselect_b32 s88, s57, s36
	s_cselect_b32 s89, s27, s37
	s_cselect_b32 s86, vcc_lo, vcc_hi
	s_cselect_b32 s87, s25, s65
	s_add_u32 s46, s88, 0x8000
	s_addc_u32 s47, s89, 0
	s_add_i32 s96, 0, 0x10000
	v_add_u32_e32 v0, s96, v192
	s_add_i32 s97, 0, 0x14000
	ds_read_b128 v[130:133], v0
	ds_read_b128 v[134:137], v0 offset:1024
	ds_read_b128 v[138:141], v0 offset:2048
	ds_read_b128 v[142:145], v0 offset:3072
	v_add_u32_e32 v0, s97, v192
	ds_read_b128 v[146:149], v0
	ds_read_b128 v[150:153], v0 offset:1024
	ds_read_b128 v[154:157], v0 offset:2048
	ds_read_b128 v[170:173], v0 offset:3072
	s_add_i32 m0, s48, 0xc000
	ds_read_b128 v[174:177], v193
	ds_read_b128 v[178:181], v193 offset:1024
	ds_read_b128 v[182:185], v193 offset:2048
	ds_read_b128 v[186:189], v193 offset:3072
	ds_read_b128 v[194:197], v193 offset:4096
	ds_read_b128 v[198:201], v193 offset:5120
	ds_read_b128 v[202:205], v193 offset:6144
	ds_read_b128 v[206:209], v193 offset:7168
	global_load_lds_dwordx4 v166, s[34:35]
	s_add_i32 m0, s48, 0xe000
	s_nop 0
	global_load_lds_dwordx4 v168, s[34:35]
	s_waitcnt vmcnt(8)
	s_waitcnt lgkmcnt(0)
	s_barrier
	s_setprio 1
	s_waitcnt lgkmcnt(0)
	v_mfma_f32_16x16x32_bf16 v[126:129], v[130:133], v[174:177], v[126:129]
	v_mfma_f32_16x16x32_bf16 v[126:129], v[134:137], v[178:181], v[126:129]
	v_mfma_f32_16x16x32_bf16 v[122:125], v[142:145], v[178:181], v[122:125]
	v_mfma_f32_16x16x32_bf16 v[122:125], v[138:141], v[174:177], v[122:125]
	v_mfma_f32_16x16x32_bf16 v[114:117], v[138:141], v[182:185], v[114:117]
	v_mfma_f32_16x16x32_bf16 v[114:117], v[142:145], v[186:189], v[114:117]
	v_mfma_f32_16x16x32_bf16 v[118:121], v[134:137], v[186:189], v[118:121]
	v_mfma_f32_16x16x32_bf16 v[118:121], v[130:133], v[182:185], v[118:121]
	v_mfma_f32_16x16x32_bf16 v[110:113], v[130:133], v[194:197], v[110:113]
	v_mfma_f32_16x16x32_bf16 v[110:113], v[134:137], v[198:201], v[110:113]
	v_mfma_f32_16x16x32_bf16 v[106:109], v[142:145], v[198:201], v[106:109]
	v_mfma_f32_16x16x32_bf16 v[106:109], v[138:141], v[194:197], v[106:109]
	v_mfma_f32_16x16x32_bf16 v[98:101], v[138:141], v[202:205], v[98:101]
	v_mfma_f32_16x16x32_bf16 v[98:101], v[142:145], v[206:209], v[98:101]
	v_mfma_f32_16x16x32_bf16 v[102:105], v[134:137], v[206:209], v[102:105]
	v_mfma_f32_16x16x32_bf16 v[102:105], v[130:133], v[202:205], v[102:105]
	s_setprio 0
	s_setprio 1
	v_mfma_f32_16x16x32_bf16 v[30:33], v[146:149], v[174:177], v[30:33]
	v_mfma_f32_16x16x32_bf16 v[30:33], v[150:153], v[178:181], v[30:33]
	v_mfma_f32_16x16x32_bf16 v[46:49], v[170:173], v[178:181], v[46:49]
	v_mfma_f32_16x16x32_bf16 v[46:49], v[154:157], v[174:177], v[46:49]
	v_mfma_f32_16x16x32_bf16 v[34:37], v[154:157], v[182:185], v[34:37]
	v_mfma_f32_16x16x32_bf16 v[34:37], v[170:173], v[186:189], v[34:37]
	v_mfma_f32_16x16x32_bf16 v[26:29], v[150:153], v[186:189], v[26:29]
	v_mfma_f32_16x16x32_bf16 v[26:29], v[146:149], v[182:185], v[26:29]
	v_mfma_f32_16x16x32_bf16 v[94:97], v[146:149], v[194:197], v[94:97]
	v_mfma_f32_16x16x32_bf16 v[94:97], v[150:153], v[198:201], v[94:97]
	v_mfma_f32_16x16x32_bf16 v[90:93], v[170:173], v[198:201], v[90:93]
	v_mfma_f32_16x16x32_bf16 v[90:93], v[154:157], v[194:197], v[90:93]
	v_mfma_f32_16x16x32_bf16 v[82:85], v[154:157], v[202:205], v[82:85]
	v_mfma_f32_16x16x32_bf16 v[82:85], v[170:173], v[206:209], v[82:85]
	v_mfma_f32_16x16x32_bf16 v[86:89], v[150:153], v[206:209], v[86:89]
	v_mfma_f32_16x16x32_bf16 v[86:89], v[146:149], v[202:205], v[86:89]
	s_setprio 0
	s_barrier
	s_add_i32 s34, s96, s44
	s_mov_b32 m0, s34
	ds_read_b128 v[174:177], v193 offset:16384
	ds_read_b128 v[178:181], v193 offset:17408
	ds_read_b128 v[182:185], v193 offset:18432
	ds_read_b128 v[186:189], v193 offset:19456
	ds_read_b128 v[194:197], v193 offset:20480
	ds_read_b128 v[198:201], v193 offset:21504
	ds_read_b128 v[202:205], v193 offset:22528
	ds_read_b128 v[206:209], v193 offset:23552
	global_load_lds_dwordx4 v162, s[86:87]
	s_add_i32 m0, s34, 0x2000
	s_add_u32 s34, s86, 0x4000
	s_addc_u32 s35, s87, 0
	s_add_i32 s96, s97, s44
	global_load_lds_dwordx4 v158, s[86:87]
	s_mov_b32 m0, s96
	v_lshl_add_u64 v[210:211], s[88:89], 0, v[160:161]
	global_load_lds_dwordx4 v162, s[34:35]
	s_add_i32 m0, s96, 0x2000
	s_nop 0
	global_load_lds_dwordx4 v158, s[34:35]
	v_lshl_add_u64 v[190:191], s[88:89], 0, v[164:165]
	s_mov_b32 m0, s48
	s_nop 0
	global_load_lds_dwordx4 v[190:191], off
	s_mov_b32 m0, s49
	s_nop 0
	global_load_lds_dwordx4 v[210:211], off
	s_waitcnt vmcnt(8)
	s_waitcnt lgkmcnt(0)
	s_barrier
; #define PG8_STAGE(bufoff, gbase, voff) do { _Pragma("unroll") for (int _i = 0; _i < 2; ++_i) \
;         __builtin_amdgcn_global_load_lds((const unsigned*)((const char*)(gbase) + (voff)[_i]), (PG8_LAS unsigned*)(lds + (bufoff) + ldsw + _i * 8192), 16, 0, 0); } while (0)
; #define PG8_LDA(dst, b, h) do { _Pragma("unroll") for (int m = 0; m < 4; ++m) _Pragma("unroll") for (int k = 0; k < 2; ++k) dst[m][k] = *(const PG8_LAS bf16x8*)(lds + PG8_SA(b, h) + aoff + m * 2048 + k * 1024); } while (0)
; #define PG8_LDB(dst, b, h) do { _Pragma("unroll") for (int n = 0; n < 2; ++n) _Pragma("unroll") for (int k = 0; k < 2; ++k) dst[n][k] = *(const PG8_LAS bf16x8*)(lds + PG8_SB(b, h) + boff + n * 2048 + k * 1024); } while (0)
; #define PG8_MMA(ai, bj, At, Bt) do { __builtin_amdgcn_s_setprio(1); _Pragma("unroll") for (int m = 0; m < 4; ++m) _Pragma("unroll") for (int n = 0; n < 2; ++n) _Pragma("unroll") for (int k = 0; k < 2; ++k) \
;         acc[ai][bj][m][n] = __builtin_amdgcn_mfma_f32_16x16x32_bf16(Bt[n][k], At[m][k], acc[ai][bj][m][n], 0, 0, 0); __builtin_amdgcn_s_setprio(0); } while (0)
; #define PG8_WAIT_V(n) asm volatile("s_waitcnt vmcnt(" #n ")" ::: "memory")
; #define PG8_WAIT_L(n) asm volatile("s_waitcnt lgkmcnt(" #n ")" ::: "memory")
; #define PG8_BAR __builtin_amdgcn_s_barrier()
; #define PG8_SCHED __builtin_amdgcn_sched_barrier(0)
;     ...
;             PG8_WAIT_V(8); PG8_WAIT_L(0); PG8_BAR; PG8_MMA(1, 0, At, B0); PG8_MMA(1, 1, At, B1); PG8_BAR; PG8_SCHED;
;             PG8_LDB(B0, 1, 0); PG8_LDB(B1, 1, 1); PG8_SCHED; PG8_LDA(At, 1, 0); PG8_STAGE(PG8_SA(0, 1), a2 + hstepA, voffA);
;             PG8_WAIT_V(8); PG8_WAIT_L(0); PG8_BAR; PG8_MMA(0, 0, At, B0); PG8_MMA(0, 1, At, B1); PG8_BAR; PG8_SCHED;
	s_setprio 1
	s_waitcnt lgkmcnt(0)
	v_mfma_f32_16x16x32_bf16 v[78:81], v[130:133], v[174:177], v[78:81]
	v_mfma_f32_16x16x32_bf16 v[78:81], v[134:137], v[178:181], v[78:81]
	v_mfma_f32_16x16x32_bf16 v[74:77], v[142:145], v[178:181], v[74:77]
	v_mfma_f32_16x16x32_bf16 v[74:77], v[138:141], v[174:177], v[74:77]
	v_mfma_f32_16x16x32_bf16 v[66:69], v[138:141], v[182:185], v[66:69]
	v_mfma_f32_16x16x32_bf16 v[66:69], v[142:145], v[186:189], v[66:69]
	v_mfma_f32_16x16x32_bf16 v[70:73], v[134:137], v[186:189], v[70:73]
	v_mfma_f32_16x16x32_bf16 v[70:73], v[130:133], v[182:185], v[70:73]
	v_mfma_f32_16x16x32_bf16 v[42:45], v[130:133], v[194:197], v[42:45]
	v_mfma_f32_16x16x32_bf16 v[42:45], v[134:137], v[198:201], v[42:45]
	v_mfma_f32_16x16x32_bf16 v[6:9], v[142:145], v[198:201], v[6:9]
	v_mfma_f32_16x16x32_bf16 v[6:9], v[138:141], v[194:197], v[6:9]
	v_mfma_f32_16x16x32_bf16 v[2:5], v[138:141], v[202:205], v[2:5]
	v_mfma_f32_16x16x32_bf16 v[2:5], v[142:145], v[206:209], v[2:5]
	v_mfma_f32_16x16x32_bf16 v[38:41], v[134:137], v[206:209], v[38:41]
	v_mfma_f32_16x16x32_bf16 v[38:41], v[130:133], v[202:205], v[38:41]
	s_setprio 0
	s_setprio 1
	v_mfma_f32_16x16x32_bf16 v[62:65], v[146:149], v[174:177], v[62:65]
	v_mfma_f32_16x16x32_bf16 v[62:65], v[150:153], v[178:181], v[62:65]
	v_mfma_f32_16x16x32_bf16 v[58:61], v[170:173], v[178:181], v[58:61]
	v_mfma_f32_16x16x32_bf16 v[58:61], v[154:157], v[174:177], v[58:61]
	v_mfma_f32_16x16x32_bf16 v[50:53], v[154:157], v[182:185], v[50:53]
	v_mfma_f32_16x16x32_bf16 v[50:53], v[170:173], v[186:189], v[50:53]
	v_mfma_f32_16x16x32_bf16 v[54:57], v[150:153], v[186:189], v[54:57]
	v_mfma_f32_16x16x32_bf16 v[54:57], v[146:149], v[182:185], v[54:57]
	v_mfma_f32_16x16x32_bf16 v[22:25], v[146:149], v[194:197], v[22:25]
	v_mfma_f32_16x16x32_bf16 v[22:25], v[150:153], v[198:201], v[22:25]
	v_mfma_f32_16x16x32_bf16 v[18:21], v[170:173], v[198:201], v[18:21]
	v_mfma_f32_16x16x32_bf16 v[18:21], v[154:157], v[194:197], v[18:21]
	v_mfma_f32_16x16x32_bf16 v[10:13], v[154:157], v[202:205], v[10:13]
	v_mfma_f32_16x16x32_bf16 v[10:13], v[170:173], v[206:209], v[10:13]
	v_mfma_f32_16x16x32_bf16 v[14:17], v[150:153], v[206:209], v[14:17]
	v_mfma_f32_16x16x32_bf16 v[14:17], v[146:149], v[202:205], v[14:17]
	s_setprio 0
	s_barrier
	s_add_i32 s88, 0, 0x18000
	v_add_u32_e32 v0, s88, v192
	s_add_i32 s89, 0, 0x1c000
	ds_read_b128 v[130:133], v0
	ds_read_b128 v[134:137], v0 offset:1024
	ds_read_b128 v[138:141], v0 offset:2048
	ds_read_b128 v[142:145], v0 offset:3072
	v_add_u32_e32 v0, s89, v192
	ds_read_b128 v[146:149], v0
	ds_read_b128 v[150:153], v0 offset:1024
	ds_read_b128 v[154:157], v0 offset:2048
	ds_read_b128 v[170:173], v0 offset:3072
	s_mov_b32 m0, s51
	v_lshl_add_u64 v[190:191], v[190:191], 0, s[58:59]
	ds_read_b128 v[174:177], v193 offset:32768
	ds_read_b128 v[178:181], v193 offset:33792
	ds_read_b128 v[182:185], v193 offset:34816
	ds_read_b128 v[186:189], v193 offset:35840
	ds_read_b128 v[194:197], v193 offset:36864
	ds_read_b128 v[198:201], v193 offset:37888
	ds_read_b128 v[202:205], v193 offset:38912
	ds_read_b128 v[206:209], v193 offset:39936
	global_load_lds_dwordx4 v[190:191], off
	v_lshl_add_u64 v[190:191], v[210:211], 0, s[58:59]
	s_mov_b32 m0, s54
	s_nop 0
	global_load_lds_dwordx4 v[190:191], off
	s_waitcnt vmcnt(8)
	s_waitcnt lgkmcnt(0)
	s_barrier
	s_setprio 1
	s_waitcnt lgkmcnt(0)
	v_mfma_f32_16x16x32_bf16 v[126:129], v[130:133], v[174:177], v[126:129]
	v_mfma_f32_16x16x32_bf16 v[126:129], v[134:137], v[178:181], v[126:129]
	v_mfma_f32_16x16x32_bf16 v[122:125], v[142:145], v[178:181], v[122:125]
	v_mfma_f32_16x16x32_bf16 v[122:125], v[138:141], v[174:177], v[122:125]
	v_mfma_f32_16x16x32_bf16 v[114:117], v[138:141], v[182:185], v[114:117]
	v_mfma_f32_16x16x32_bf16 v[114:117], v[142:145], v[186:189], v[114:117]
	v_mfma_f32_16x16x32_bf16 v[118:121], v[134:137], v[186:189], v[118:121]
	v_mfma_f32_16x16x32_bf16 v[118:121], v[130:133], v[182:185], v[118:121]
	v_mfma_f32_16x16x32_bf16 v[110:113], v[130:133], v[194:197], v[110:113]
	v_mfma_f32_16x16x32_bf16 v[110:113], v[134:137], v[198:201], v[110:113]
	v_mfma_f32_16x16x32_bf16 v[106:109], v[142:145], v[198:201], v[106:109]
	v_mfma_f32_16x16x32_bf16 v[106:109], v[138:141], v[194:197], v[106:109]
	v_mfma_f32_16x16x32_bf16 v[98:101], v[138:141], v[202:205], v[98:101]
	v_mfma_f32_16x16x32_bf16 v[98:101], v[142:145], v[206:209], v[98:101]
	v_mfma_f32_16x16x32_bf16 v[102:105], v[134:137], v[206:209], v[102:105]
	v_mfma_f32_16x16x32_bf16 v[102:105], v[130:133], v[202:205], v[102:105]
	s_setprio 0
	s_setprio 1
	v_mfma_f32_16x16x32_bf16 v[30:33], v[146:149], v[174:177], v[30:33]
	v_mfma_f32_16x16x32_bf16 v[30:33], v[150:153], v[178:181], v[30:33]
	v_mfma_f32_16x16x32_bf16 v[46:49], v[170:173], v[178:181], v[46:49]
	v_mfma_f32_16x16x32_bf16 v[46:49], v[154:157], v[174:177], v[46:49]
	v_mfma_f32_16x16x32_bf16 v[34:37], v[154:157], v[182:185], v[34:37]
	v_mfma_f32_16x16x32_bf16 v[34:37], v[170:173], v[186:189], v[34:37]
	v_mfma_f32_16x16x32_bf16 v[26:29], v[150:153], v[186:189], v[26:29]
	v_mfma_f32_16x16x32_bf16 v[26:29], v[146:149], v[182:185], v[26:29]
	v_mfma_f32_16x16x32_bf16 v[94:97], v[146:149], v[194:197], v[94:97]
	v_mfma_f32_16x16x32_bf16 v[94:97], v[150:153], v[198:201], v[94:97]
	v_mfma_f32_16x16x32_bf16 v[90:93], v[170:173], v[198:201], v[90:93]
	v_mfma_f32_16x16x32_bf16 v[90:93], v[154:157], v[194:197], v[90:93]
	v_mfma_f32_16x16x32_bf16 v[82:85], v[154:157], v[202:205], v[82:85]
	v_mfma_f32_16x16x32_bf16 v[82:85], v[170:173], v[206:209], v[82:85]
	v_mfma_f32_16x16x32_bf16 v[86:89], v[150:153], v[206:209], v[86:89]
	v_mfma_f32_16x16x32_bf16 v[86:89], v[146:149], v[202:205], v[86:89]
	s_setprio 0
	s_barrier
; #define PG8_STAGE(bufoff, gbase, voff) do { _Pragma("unroll") for (int _i = 0; _i < 2; ++_i) \
;         __builtin_amdgcn_global_load_lds((const unsigned*)((const char*)(gbase) + (voff)[_i]), (PG8_LAS unsigned*)(lds + (bufoff) + ldsw + _i * 8192), 16, 0, 0); } while (0)
; #define PG8_LDA(dst, b, h) do { _Pragma("unroll") for (int m = 0; m < 4; ++m) _Pragma("unroll") for (int k = 0; k < 2; ++k) dst[m][k] = *(const PG8_LAS bf16x8*)(lds + PG8_SA(b, h) + aoff + m * 2048 + k * 1024); } while (0)
; #define PG8_MMA(ai, bj, At, Bt) do { __builtin_amdgcn_s_setprio(1); _Pragma("unroll") for (int m = 0; m < 4; ++m) _Pragma("unroll") for (int n = 0; n < 2; ++n) _Pragma("unroll") for (int k = 0; k < 2; ++k) \
;         acc[ai][bj][m][n] = __builtin_amdgcn_mfma_f32_16x16x32_bf16(Bt[n][k], At[m][k], acc[ai][bj][m][n], 0, 0, 0); __builtin_amdgcn_s_setprio(0); } while (0)
; #define PG8_WAIT_V(n) asm volatile("s_waitcnt vmcnt(" #n ")" ::: "memory")
; #define PG8_WAIT_L(n) asm volatile("s_waitcnt lgkmcnt(" #n ")" ::: "memory")
; #define PG8_BAR __builtin_amdgcn_s_barrier()
; #define PG8_SCHED __builtin_amdgcn_sched_barrier(0)
;     ...
;         for (int t = 0; t < nt; t += 2) {
;             const bool last = (t == nt - 2);
;             const char* a1 = cA + (ptrdiff_t)(t + 1) * kstepA;
;             const char* a2 = last ? nA : cA + (ptrdiff_t)(t + 2) * kstepA; const char* b2 = last ? nB : cB + (ptrdiff_t)(t + 2) * kstep;
;     ...
;             PG8_LDA(At, 1, 1); PG8_STAGE(PG8_SB(1, 0), b3, voffB); PG8_STAGE(PG8_SB(1, 1), b3 + hstepB, voffB); PG8_STAGE(PG8_SA(1, 0), a3, voffA);
;             PG8_WAIT_V(8); PG8_WAIT_L(0); PG8_BAR; PG8_MMA(1, 0, At, B0); PG8_MMA(1, 1, At, B1); PG8_BAR; PG8_SCHED;
	s_add_u32 s34, s86, 0x8000
	s_addc_u32 s35, s87, 0
	s_add_i32 s88, s88, s44
	s_mov_b32 m0, s88
	ds_read_b128 v[174:177], v193 offset:49152
	ds_read_b128 v[178:181], v193 offset:50176
	ds_read_b128 v[182:185], v193 offset:51200
	ds_read_b128 v[186:189], v193 offset:52224
	ds_read_b128 v[194:197], v193 offset:53248
	ds_read_b128 v[198:201], v193 offset:54272
	ds_read_b128 v[202:205], v193 offset:55296
	ds_read_b128 v[206:209], v193 offset:56320
	global_load_lds_dwordx4 v162, s[34:35]
	s_add_i32 m0, s88, 0x2000
	v_lshl_add_u64 v[190:191], s[34:35], 0, v[158:159]
	s_add_u32 s34, s86, 0xc000
	s_addc_u32 s35, s87, 0
	s_add_i32 s86, s89, s44
	global_load_lds_dwordx4 v[190:191], off
	s_mov_b32 m0, s86
	s_nop 0
	global_load_lds_dwordx4 v162, s[34:35]
	s_add_i32 m0, s86, 0x2000
	s_nop 0
	global_load_lds_dwordx4 v158, s[34:35]
	s_mov_b32 m0, s85
	s_nop 0
	global_load_lds_dwordx4 v164, s[46:47]
	v_lshl_add_u64 v[190:191], s[46:47], 0, v[160:161]
	s_mov_b32 m0, s90
	s_nop 0
	global_load_lds_dwordx4 v[190:191], off
	s_waitcnt vmcnt(8)
	s_waitcnt lgkmcnt(0)
	s_barrier
	s_setprio 1
	s_waitcnt lgkmcnt(0)
	v_mfma_f32_16x16x32_bf16 v[78:81], v[130:133], v[174:177], v[78:81]
	v_mfma_f32_16x16x32_bf16 v[78:81], v[134:137], v[178:181], v[78:81]
	v_mfma_f32_16x16x32_bf16 v[74:77], v[142:145], v[178:181], v[74:77]
	v_mfma_f32_16x16x32_bf16 v[74:77], v[138:141], v[174:177], v[74:77]
	v_mfma_f32_16x16x32_bf16 v[66:69], v[138:141], v[182:185], v[66:69]
	v_mfma_f32_16x16x32_bf16 v[66:69], v[142:145], v[186:189], v[66:69]
	v_mfma_f32_16x16x32_bf16 v[70:73], v[134:137], v[186:189], v[70:73]
	v_mfma_f32_16x16x32_bf16 v[70:73], v[130:133], v[182:185], v[70:73]
	v_mfma_f32_16x16x32_bf16 v[42:45], v[130:133], v[194:197], v[42:45]
	v_mfma_f32_16x16x32_bf16 v[42:45], v[134:137], v[198:201], v[42:45]
	v_mfma_f32_16x16x32_bf16 v[6:9], v[142:145], v[198:201], v[6:9]
	v_mfma_f32_16x16x32_bf16 v[6:9], v[138:141], v[194:197], v[6:9]
	v_mfma_f32_16x16x32_bf16 v[2:5], v[138:141], v[202:205], v[2:5]
	v_mfma_f32_16x16x32_bf16 v[2:5], v[142:145], v[206:209], v[2:5]
	v_mfma_f32_16x16x32_bf16 v[38:41], v[134:137], v[206:209], v[38:41]
	v_mfma_f32_16x16x32_bf16 v[38:41], v[130:133], v[202:205], v[38:41]
	s_setprio 0
	s_setprio 1
	v_mfma_f32_16x16x32_bf16 v[62:65], v[146:149], v[174:177], v[62:65]
	v_mfma_f32_16x16x32_bf16 v[62:65], v[150:153], v[178:181], v[62:65]
	v_mfma_f32_16x16x32_bf16 v[58:61], v[170:173], v[178:181], v[58:61]
	v_mfma_f32_16x16x32_bf16 v[58:61], v[154:157], v[174:177], v[58:61]
	v_mfma_f32_16x16x32_bf16 v[50:53], v[154:157], v[182:185], v[50:53]
	v_mfma_f32_16x16x32_bf16 v[50:53], v[170:173], v[186:189], v[50:53]
	v_mfma_f32_16x16x32_bf16 v[54:57], v[150:153], v[186:189], v[54:57]
	v_mfma_f32_16x16x32_bf16 v[54:57], v[146:149], v[182:185], v[54:57]
	v_mfma_f32_16x16x32_bf16 v[22:25], v[146:149], v[194:197], v[22:25]
	v_mfma_f32_16x16x32_bf16 v[22:25], v[150:153], v[198:201], v[22:25]
	v_mfma_f32_16x16x32_bf16 v[18:21], v[170:173], v[198:201], v[18:21]
	v_mfma_f32_16x16x32_bf16 v[18:21], v[154:157], v[194:197], v[18:21]
	v_mfma_f32_16x16x32_bf16 v[10:13], v[154:157], v[202:205], v[10:13]
	v_mfma_f32_16x16x32_bf16 v[10:13], v[170:173], v[206:209], v[10:13]
	v_mfma_f32_16x16x32_bf16 v[14:17], v[150:153], v[206:209], v[14:17]
	v_mfma_f32_16x16x32_bf16 v[14:17], v[146:149], v[202:205], v[14:17]
	s_setprio 0
	s_barrier
	s_add_i32 s66, s66, 2
	s_add_u32 vcc_hi, vcc_hi, 0x10000
	s_addc_u32 s65, s65, 0
	s_cmp_gt_u32 s66, 29
	s_mov_b64 s[34:35], s[36:37]
	s_cbranch_scc0 .LBB0_1256
	s_and_b64 vcc, exec, s[18:19]
	s_cbranch_vccz .LBB0_1259
	s_barrier

; #define PG8_STAGE(bufoff, gbase, voff) do { _Pragma("unroll") for (int _i = 0; _i < 2; ++_i) \
;         __builtin_amdgcn_global_load_lds((const unsigned*)((const char*)(gbase) + (voff)[_i]), (PG8_LAS unsigned*)(lds + (bufoff) + ldsw + _i * 8192), 16, 0, 0); } while (0)
; #define PG8_LDA(dst, b, h) do { _Pragma("unroll") for (int m = 0; m < 4; ++m) _Pragma("unroll") for (int k = 0; k < 2; ++k) dst[m][k] = *(const PG8_LAS bf16x8*)(lds + PG8_SA(b, h) + aoff + m * 2048 + k * 1024); } while (0)
; #define PG8_LDB(dst, b, h) do { _Pragma("unroll") for (int n = 0; n < 2; ++n) _Pragma("unroll") for (int k = 0; k < 2; ++k) dst[n][k] = *(const PG8_LAS bf16x8*)(lds + PG8_SB(b, h) + boff + n * 2048 + k * 1024); } while (0)
; #define PG8_MMA(ai, bj, At, Bt) do { __builtin_amdgcn_s_setprio(1); _Pragma("unroll") for (int m = 0; m < 4; ++m) _Pragma("unroll") for (int n = 0; n < 2; ++n) _Pragma("unroll") for (int k = 0; k < 2; ++k) \
;         acc[ai][bj][m][n] = __builtin_amdgcn_mfma_f32_16x16x32_bf16(Bt[n][k], At[m][k], acc[ai][bj][m][n], 0, 0, 0); __builtin_amdgcn_s_setprio(0); } while (0)
; #define PG8_WAIT_V(n) asm volatile("s_waitcnt vmcnt(" #n ")" ::: "memory")
; #define PG8_WAIT_L(n) asm volatile("s_waitcnt lgkmcnt(" #n ")" ::: "memory")
; #define PG8_BAR __builtin_amdgcn_s_barrier()
; #define PG8_SCHED __builtin_amdgcn_sched_barrier(0)
;     ...
;             const char* a1 = cA + (ptrdiff_t)(t + 1) * kstepA;
;             const char* a2 = last ? nA : cA + (ptrdiff_t)(t + 2) * kstepA; const char* b2 = last ? nB : cB + (ptrdiff_t)(t + 2) * kstep;
;             const char* a3 = a2 + kstepA; const char* b3 = b2 + kstep;
;             if (last && has_next) S.a_ready(nxt);
;             if constexpr (SP2) {
;             PG8_LDB(B0, 0, 0); PG8_LDB(B1, 0, 1); PG8_SCHED; PG8_LDA(At, 0, 0); PG8_STAGE(PG8_SA(1, 1), a1 + hstepA, voffA);
;             PG8_WAIT_V(8); PG8_WAIT_L(0); PG8_BAR; PG8_MMA(0, 0, At, B0); PG8_MMA(0, 1, At, B1); PG8_BAR; PG8_SCHED;
;             PG8_LDA(At, 0, 1); PG8_STAGE(PG8_SB(0, 0), b2, voffB); PG8_STAGE(PG8_SB(0, 1), b2 + hstepB, voffB); PG8_STAGE(PG8_SA(0, 0), a2, voffA);
;             PG8_WAIT_V(8); PG8_WAIT_L(0); PG8_BAR; PG8_MMA(1, 0, At, B0); PG8_MMA(1, 1, At, B1); PG8_BAR; PG8_SCHED;
.LBB0_1444:
	s_or_b32 s44, s56, 1
	s_lshl_b64 s[34:35], s[44:45], 15
	s_sub_u32 s34, 0, s34
	s_subb_u32 s35, 0, s35
	s_add_u32 s44, s28, s34
	s_addc_u32 s65, s29, s35
	s_add_u32 s34, s30, 0xffff8000
	s_addc_u32 s35, s31, -1
	s_add_i32 s66, 0, 0x10000
	v_add_u32_e32 v0, s66, v230
	s_add_i32 s90, 0, 0x14000
	s_waitcnt lgkmcnt(0)
	ds_read_b128 v[130:133], v0
	ds_read_b128 v[134:137], v0 offset:1024
	ds_read_b128 v[138:141], v0 offset:2048
	ds_read_b128 v[142:145], v0 offset:3072
	v_add_u32_e32 v0, s90, v230
	ds_read_b128 v[146:149], v0
	ds_read_b128 v[150:153], v0 offset:1024
	ds_read_b128 v[154:157], v0 offset:2048
	ds_read_b128 v[158:161], v0 offset:3072
	s_add_u32 s88, s44, 0x4000
	s_addc_u32 s89, s65, 0
	s_add_i32 m0, s46, 0xc000
	ds_read_b128 v[162:165], v231
	ds_read_b128 v[166:169], v231 offset:1024
	ds_read_b128 v[170:173], v231 offset:2048
	ds_read_b128 v[174:177], v231 offset:3072
	ds_read_b128 v[178:181], v231 offset:4096
	ds_read_b128 v[182:185], v231 offset:5120
	ds_read_b128 v[186:189], v231 offset:6144
	ds_read_b128 v[190:193], v231 offset:7168
	global_load_lds_dwordx4 v194, s[88:89]
	s_add_i32 m0, s46, 0xe000
	s_nop 0
	global_load_lds_dwordx4 v198, s[88:89]
	s_waitcnt vmcnt(8)
	s_waitcnt lgkmcnt(0)
	s_barrier
	s_setprio 1
	s_waitcnt lgkmcnt(0)
	v_mfma_f32_16x16x32_bf16 v[126:129], v[130:133], v[162:165], v[126:129]
	v_mfma_f32_16x16x32_bf16 v[126:129], v[134:137], v[166:169], v[126:129]
	v_mfma_f32_16x16x32_bf16 v[122:125], v[142:145], v[166:169], v[122:125]
	v_mfma_f32_16x16x32_bf16 v[122:125], v[138:141], v[162:165], v[122:125]
	v_mfma_f32_16x16x32_bf16 v[106:109], v[138:141], v[170:173], v[106:109]
	v_mfma_f32_16x16x32_bf16 v[106:109], v[142:145], v[174:177], v[106:109]
	v_mfma_f32_16x16x32_bf16 v[110:113], v[134:137], v[174:177], v[110:113]
	v_mfma_f32_16x16x32_bf16 v[110:113], v[130:133], v[170:173], v[110:113]
	v_mfma_f32_16x16x32_bf16 v[94:97], v[130:133], v[178:181], v[94:97]
	v_mfma_f32_16x16x32_bf16 v[94:97], v[134:137], v[182:185], v[94:97]
	v_mfma_f32_16x16x32_bf16 v[90:93], v[142:145], v[182:185], v[90:93]
	v_mfma_f32_16x16x32_bf16 v[90:93], v[138:141], v[178:181], v[90:93]
	v_mfma_f32_16x16x32_bf16 v[74:77], v[138:141], v[186:189], v[74:77]
	v_mfma_f32_16x16x32_bf16 v[74:77], v[142:145], v[190:193], v[74:77]
	v_mfma_f32_16x16x32_bf16 v[78:81], v[134:137], v[190:193], v[78:81]
	v_mfma_f32_16x16x32_bf16 v[78:81], v[130:133], v[186:189], v[78:81]
	s_setprio 0
	s_setprio 1
	v_mfma_f32_16x16x32_bf16 v[118:121], v[146:149], v[162:165], v[118:121]
	v_mfma_f32_16x16x32_bf16 v[118:121], v[150:153], v[166:169], v[118:121]
	v_mfma_f32_16x16x32_bf16 v[114:117], v[158:161], v[166:169], v[114:117]
	v_mfma_f32_16x16x32_bf16 v[114:117], v[154:157], v[162:165], v[114:117]
	v_mfma_f32_16x16x32_bf16 v[98:101], v[154:157], v[170:173], v[98:101]
	v_mfma_f32_16x16x32_bf16 v[98:101], v[158:161], v[174:177], v[98:101]
	v_mfma_f32_16x16x32_bf16 v[102:105], v[150:153], v[174:177], v[102:105]
	v_mfma_f32_16x16x32_bf16 v[102:105], v[146:149], v[170:173], v[102:105]
	v_mfma_f32_16x16x32_bf16 v[86:89], v[146:149], v[178:181], v[86:89]
	v_mfma_f32_16x16x32_bf16 v[86:89], v[150:153], v[182:185], v[86:89]
	v_mfma_f32_16x16x32_bf16 v[82:85], v[158:161], v[182:185], v[82:85]
	v_mfma_f32_16x16x32_bf16 v[82:85], v[154:157], v[178:181], v[82:85]
	v_mfma_f32_16x16x32_bf16 v[66:69], v[154:157], v[186:189], v[66:69]
	v_mfma_f32_16x16x32_bf16 v[66:69], v[158:161], v[190:193], v[66:69]
	v_mfma_f32_16x16x32_bf16 v[70:73], v[150:153], v[190:193], v[70:73]
	v_mfma_f32_16x16x32_bf16 v[70:73], v[146:149], v[186:189], v[70:73]
	s_setprio 0
	s_barrier
	s_add_i32 s44, s66, s41
	s_mov_b32 m0, s44
	ds_read_b128 v[162:165], v231 offset:16384
	ds_read_b128 v[166:169], v231 offset:17408
	ds_read_b128 v[170:173], v231 offset:18432
	ds_read_b128 v[174:177], v231 offset:19456
	ds_read_b128 v[178:181], v231 offset:20480
	ds_read_b128 v[182:185], v231 offset:21504
	ds_read_b128 v[186:189], v231 offset:22528
	ds_read_b128 v[190:193], v231 offset:23552
	global_load_lds_dwordx4 v196, s[8:9]
	s_add_i32 m0, s44, 0x2000
	s_add_u32 s88, s8, 0x4000
	s_addc_u32 s89, s9, 0
	s_add_i32 s44, s90, s41
	global_load_lds_dwordx4 v200, s[8:9]
	s_mov_b32 m0, s44
	s_nop 0
	global_load_lds_dwordx4 v196, s[88:89]
	s_add_i32 m0, s44, 0x2000
	s_nop 0
	global_load_lds_dwordx4 v200, s[88:89]
	s_mov_b32 m0, s46
	s_nop 0
	global_load_lds_dwordx4 v194, s[30:31]
	s_mov_b32 m0, s47
	s_nop 0
	global_load_lds_dwordx4 v198, s[30:31]
	s_waitcnt vmcnt(8)
	s_waitcnt lgkmcnt(0)
	s_barrier
; #define PG8_STAGE(bufoff, gbase, voff) do { _Pragma("unroll") for (int _i = 0; _i < 2; ++_i) \
;         __builtin_amdgcn_global_load_lds((const unsigned*)((const char*)(gbase) + (voff)[_i]), (PG8_LAS unsigned*)(lds + (bufoff) + ldsw + _i * 8192), 16, 0, 0); } while (0)
; #define PG8_LDA(dst, b, h) do { _Pragma("unroll") for (int m = 0; m < 4; ++m) _Pragma("unroll") for (int k = 0; k < 2; ++k) dst[m][k] = *(const PG8_LAS bf16x8*)(lds + PG8_SA(b, h) + aoff + m * 2048 + k * 1024); } while (0)
; #define PG8_LDB(dst, b, h) do { _Pragma("unroll") for (int n = 0; n < 2; ++n) _Pragma("unroll") for (int k = 0; k < 2; ++k) dst[n][k] = *(const PG8_LAS bf16x8*)(lds + PG8_SB(b, h) + boff + n * 2048 + k * 1024); } while (0)
; #define PG8_MMA(ai, bj, At, Bt) do { __builtin_amdgcn_s_setprio(1); _Pragma("unroll") for (int m = 0; m < 4; ++m) _Pragma("unroll") for (int n = 0; n < 2; ++n) _Pragma("unroll") for (int k = 0; k < 2; ++k) \
;         acc[ai][bj][m][n] = __builtin_amdgcn_mfma_f32_16x16x32_bf16(Bt[n][k], At[m][k], acc[ai][bj][m][n], 0, 0, 0); __builtin_amdgcn_s_setprio(0); } while (0)
; #define PG8_WAIT_V(n) asm volatile("s_waitcnt vmcnt(" #n ")" ::: "memory")
; #define PG8_WAIT_L(n) asm volatile("s_waitcnt lgkmcnt(" #n ")" ::: "memory")
; #define PG8_BAR __builtin_amdgcn_s_barrier()
; #define PG8_SCHED __builtin_amdgcn_sched_barrier(0)
;     ...
;             PG8_WAIT_V(8); PG8_WAIT_L(0); PG8_BAR; PG8_MMA(1, 0, At, B0); PG8_MMA(1, 1, At, B1); PG8_BAR; PG8_SCHED;
;             PG8_LDB(B0, 1, 0); PG8_LDB(B1, 1, 1); PG8_SCHED; PG8_LDA(At, 1, 0); PG8_STAGE(PG8_SA(0, 1), a2 + hstepA, voffA);
;             PG8_WAIT_V(8); PG8_WAIT_L(0); PG8_BAR; PG8_MMA(0, 0, At, B0); PG8_MMA(0, 1, At, B1); PG8_BAR; PG8_SCHED;
	s_setprio 1
	s_waitcnt lgkmcnt(0)
	v_mfma_f32_16x16x32_bf16 v[62:65], v[130:133], v[162:165], v[62:65]
	v_mfma_f32_16x16x32_bf16 v[62:65], v[134:137], v[166:169], v[62:65]
	v_mfma_f32_16x16x32_bf16 v[58:61], v[142:145], v[166:169], v[58:61]
	v_mfma_f32_16x16x32_bf16 v[58:61], v[138:141], v[162:165], v[58:61]
	v_mfma_f32_16x16x32_bf16 v[42:45], v[138:141], v[170:173], v[42:45]
	v_mfma_f32_16x16x32_bf16 v[42:45], v[142:145], v[174:177], v[42:45]
	v_mfma_f32_16x16x32_bf16 v[46:49], v[134:137], v[174:177], v[46:49]
	v_mfma_f32_16x16x32_bf16 v[46:49], v[130:133], v[170:173], v[46:49]
	v_mfma_f32_16x16x32_bf16 v[30:33], v[130:133], v[178:181], v[30:33]
	v_mfma_f32_16x16x32_bf16 v[30:33], v[134:137], v[182:185], v[30:33]
	v_mfma_f32_16x16x32_bf16 v[26:29], v[142:145], v[182:185], v[26:29]
	v_mfma_f32_16x16x32_bf16 v[26:29], v[138:141], v[178:181], v[26:29]
	v_mfma_f32_16x16x32_bf16 v[10:13], v[138:141], v[186:189], v[10:13]
	v_mfma_f32_16x16x32_bf16 v[10:13], v[142:145], v[190:193], v[10:13]
	v_mfma_f32_16x16x32_bf16 v[14:17], v[134:137], v[190:193], v[14:17]
	v_mfma_f32_16x16x32_bf16 v[14:17], v[130:133], v[186:189], v[14:17]
	s_setprio 0
	s_setprio 1
	v_mfma_f32_16x16x32_bf16 v[54:57], v[146:149], v[162:165], v[54:57]
	v_mfma_f32_16x16x32_bf16 v[54:57], v[150:153], v[166:169], v[54:57]
	v_mfma_f32_16x16x32_bf16 v[50:53], v[158:161], v[166:169], v[50:53]
	v_mfma_f32_16x16x32_bf16 v[50:53], v[154:157], v[162:165], v[50:53]
	v_mfma_f32_16x16x32_bf16 v[34:37], v[154:157], v[170:173], v[34:37]
	v_mfma_f32_16x16x32_bf16 v[34:37], v[158:161], v[174:177], v[34:37]
	v_mfma_f32_16x16x32_bf16 v[38:41], v[150:153], v[174:177], v[38:41]
	v_mfma_f32_16x16x32_bf16 v[38:41], v[146:149], v[170:173], v[38:41]
	v_mfma_f32_16x16x32_bf16 v[22:25], v[146:149], v[178:181], v[22:25]
	v_mfma_f32_16x16x32_bf16 v[22:25], v[150:153], v[182:185], v[22:25]
	v_mfma_f32_16x16x32_bf16 v[18:21], v[158:161], v[182:185], v[18:21]
	v_mfma_f32_16x16x32_bf16 v[18:21], v[154:157], v[178:181], v[18:21]
	v_mfma_f32_16x16x32_bf16 v[2:5], v[154:157], v[186:189], v[2:5]
	v_mfma_f32_16x16x32_bf16 v[2:5], v[158:161], v[190:193], v[2:5]
	v_mfma_f32_16x16x32_bf16 v[6:9], v[150:153], v[190:193], v[6:9]
	v_mfma_f32_16x16x32_bf16 v[6:9], v[146:149], v[186:189], v[6:9]
	s_setprio 0
	s_barrier
	s_add_i32 s44, 0, 0x18000
	v_add_u32_e32 v0, s44, v230
	s_add_i32 s65, 0, 0x1c000
	ds_read_b128 v[130:133], v0
	ds_read_b128 v[134:137], v0 offset:1024
	ds_read_b128 v[138:141], v0 offset:2048
	ds_read_b128 v[142:145], v0 offset:3072
	v_add_u32_e32 v0, s65, v230
	ds_read_b128 v[146:149], v0
	ds_read_b128 v[150:153], v0 offset:1024
	ds_read_b128 v[154:157], v0 offset:2048
	ds_read_b128 v[158:161], v0 offset:3072
	s_add_u32 s30, s30, 0x4000
	s_addc_u32 s31, s31, 0
	s_mov_b32 m0, s48
	ds_read_b128 v[162:165], v231 offset:32768
	ds_read_b128 v[166:169], v231 offset:33792
	ds_read_b128 v[170:173], v231 offset:34816
	ds_read_b128 v[174:177], v231 offset:35840
	ds_read_b128 v[178:181], v231 offset:36864
	ds_read_b128 v[182:185], v231 offset:37888
	ds_read_b128 v[186:189], v231 offset:38912
	ds_read_b128 v[190:193], v231 offset:39936
	global_load_lds_dwordx4 v194, s[30:31]
	s_mov_b32 m0, s49
	s_nop 0
	global_load_lds_dwordx4 v198, s[30:31]
	s_waitcnt vmcnt(8)
	s_waitcnt lgkmcnt(0)
	s_barrier
	s_setprio 1
	s_waitcnt lgkmcnt(0)
	v_mfma_f32_16x16x32_bf16 v[126:129], v[130:133], v[162:165], v[126:129]
	v_mfma_f32_16x16x32_bf16 v[126:129], v[134:137], v[166:169], v[126:129]
	v_mfma_f32_16x16x32_bf16 v[122:125], v[142:145], v[166:169], v[122:125]
	v_mfma_f32_16x16x32_bf16 v[122:125], v[138:141], v[162:165], v[122:125]
	v_mfma_f32_16x16x32_bf16 v[106:109], v[138:141], v[170:173], v[106:109]
	v_mfma_f32_16x16x32_bf16 v[106:109], v[142:145], v[174:177], v[106:109]
	v_mfma_f32_16x16x32_bf16 v[110:113], v[134:137], v[174:177], v[110:113]
	v_mfma_f32_16x16x32_bf16 v[110:113], v[130:133], v[170:173], v[110:113]
	v_mfma_f32_16x16x32_bf16 v[94:97], v[130:133], v[178:181], v[94:97]
	v_mfma_f32_16x16x32_bf16 v[94:97], v[134:137], v[182:185], v[94:97]
	v_mfma_f32_16x16x32_bf16 v[90:93], v[142:145], v[182:185], v[90:93]
	v_mfma_f32_16x16x32_bf16 v[90:93], v[138:141], v[178:181], v[90:93]
	v_mfma_f32_16x16x32_bf16 v[74:77], v[138:141], v[186:189], v[74:77]
	v_mfma_f32_16x16x32_bf16 v[74:77], v[142:145], v[190:193], v[74:77]
	v_mfma_f32_16x16x32_bf16 v[78:81], v[134:137], v[190:193], v[78:81]
	v_mfma_f32_16x16x32_bf16 v[78:81], v[130:133], v[186:189], v[78:81]
	s_setprio 0
	s_setprio 1
	v_mfma_f32_16x16x32_bf16 v[118:121], v[146:149], v[162:165], v[118:121]
	v_mfma_f32_16x16x32_bf16 v[118:121], v[150:153], v[166:169], v[118:121]
	v_mfma_f32_16x16x32_bf16 v[114:117], v[158:161], v[166:169], v[114:117]
	v_mfma_f32_16x16x32_bf16 v[114:117], v[154:157], v[162:165], v[114:117]
	v_mfma_f32_16x16x32_bf16 v[98:101], v[154:157], v[170:173], v[98:101]
	v_mfma_f32_16x16x32_bf16 v[98:101], v[158:161], v[174:177], v[98:101]
	v_mfma_f32_16x16x32_bf16 v[102:105], v[150:153], v[174:177], v[102:105]
	v_mfma_f32_16x16x32_bf16 v[102:105], v[146:149], v[170:173], v[102:105]
	v_mfma_f32_16x16x32_bf16 v[86:89], v[146:149], v[178:181], v[86:89]
	v_mfma_f32_16x16x32_bf16 v[86:89], v[150:153], v[182:185], v[86:89]
	v_mfma_f32_16x16x32_bf16 v[82:85], v[158:161], v[182:185], v[82:85]
	v_mfma_f32_16x16x32_bf16 v[82:85], v[154:157], v[178:181], v[82:85]
	v_mfma_f32_16x16x32_bf16 v[66:69], v[154:157], v[186:189], v[66:69]
	v_mfma_f32_16x16x32_bf16 v[66:69], v[158:161], v[190:193], v[66:69]
	v_mfma_f32_16x16x32_bf16 v[70:73], v[150:153], v[190:193], v[70:73]
	v_mfma_f32_16x16x32_bf16 v[70:73], v[146:149], v[186:189], v[70:73]
	s_setprio 0
	s_barrier
; #define PG8_STAGE(bufoff, gbase, voff) do { _Pragma("unroll") for (int _i = 0; _i < 2; ++_i) \
;         __builtin_amdgcn_global_load_lds((const unsigned*)((const char*)(gbase) + (voff)[_i]), (PG8_LAS unsigned*)(lds + (bufoff) + ldsw + _i * 8192), 16, 0, 0); } while (0)
; #define PG8_LDA(dst, b, h) do { _Pragma("unroll") for (int m = 0; m < 4; ++m) _Pragma("unroll") for (int k = 0; k < 2; ++k) dst[m][k] = *(const PG8_LAS bf16x8*)(lds + PG8_SA(b, h) + aoff + m * 2048 + k * 1024); } while (0)
; #define PG8_MMA(ai, bj, At, Bt) do { __builtin_amdgcn_s_setprio(1); _Pragma("unroll") for (int m = 0; m < 4; ++m) _Pragma("unroll") for (int n = 0; n < 2; ++n) _Pragma("unroll") for (int k = 0; k < 2; ++k) \
;         acc[ai][bj][m][n] = __builtin_amdgcn_mfma_f32_16x16x32_bf16(Bt[n][k], At[m][k], acc[ai][bj][m][n], 0, 0, 0); __builtin_amdgcn_s_setprio(0); } while (0)
; #define PG8_WAIT_V(n) asm volatile("s_waitcnt vmcnt(" #n ")" ::: "memory")
; #define PG8_WAIT_L(n) asm volatile("s_waitcnt lgkmcnt(" #n ")" ::: "memory")
; #define PG8_BAR __builtin_amdgcn_s_barrier()
; #define PG8_SCHED __builtin_amdgcn_sched_barrier(0)
;     ...
;         for (int t = 0; t < nt; t += 2) {
;             const bool last = (t == nt - 2);
;             const char* a1 = cA + (ptrdiff_t)(t + 1) * kstepA;
;             const char* a2 = last ? nA : cA + (ptrdiff_t)(t + 2) * kstepA; const char* b2 = last ? nB : cB + (ptrdiff_t)(t + 2) * kstep;
;     ...
;             PG8_LDA(At, 1, 1); PG8_STAGE(PG8_SB(1, 0), b3, voffB); PG8_STAGE(PG8_SB(1, 1), b3 + hstepB, voffB); PG8_STAGE(PG8_SA(1, 0), a3, voffA);
;             PG8_WAIT_V(8); PG8_WAIT_L(0); PG8_BAR; PG8_MMA(1, 0, At, B0); PG8_MMA(1, 1, At, B1); PG8_BAR; PG8_SCHED;
	s_add_u32 s30, s8, 0xffff8000
	s_addc_u32 s31, s9, -1
	s_add_i32 s44, s44, s41
	s_mov_b32 m0, s44
	ds_read_b128 v[162:165], v231 offset:49152
	ds_read_b128 v[166:169], v231 offset:50176
	ds_read_b128 v[170:173], v231 offset:51200
	ds_read_b128 v[174:177], v231 offset:52224
	ds_read_b128 v[178:181], v231 offset:53248
	ds_read_b128 v[182:185], v231 offset:54272
	ds_read_b128 v[186:189], v231 offset:55296
	ds_read_b128 v[190:193], v231 offset:56320
	global_load_lds_dwordx4 v196, s[30:31]
	s_add_i32 m0, s44, 0x2000
	s_add_u32 s8, s8, 0xffffc000
	v_lshl_add_u64 v[202:203], s[30:31], 0, v[200:201]
	s_addc_u32 s9, s9, -1
	s_add_i32 s30, s65, s41
	global_load_lds_dwordx4 v[202:203], off
	s_mov_b32 m0, s30
	s_nop 0
	global_load_lds_dwordx4 v196, s[8:9]
	s_add_i32 m0, s30, 0x2000
	s_nop 0
	global_load_lds_dwordx4 v200, s[8:9]
	s_mov_b32 m0, s71
	s_nop 0
	global_load_lds_dwordx4 v194, s[34:35]
	v_lshl_add_u64 v[202:203], s[34:35], 0, v[198:199]
	s_mov_b32 m0, s80
	s_nop 0
	global_load_lds_dwordx4 v[202:203], off
	s_waitcnt vmcnt(8)
	s_waitcnt lgkmcnt(0)
	s_barrier
	s_setprio 1
	s_waitcnt lgkmcnt(0)
	v_mfma_f32_16x16x32_bf16 v[62:65], v[130:133], v[162:165], v[62:65]
	v_mfma_f32_16x16x32_bf16 v[62:65], v[134:137], v[166:169], v[62:65]
	v_mfma_f32_16x16x32_bf16 v[58:61], v[142:145], v[166:169], v[58:61]
	v_mfma_f32_16x16x32_bf16 v[58:61], v[138:141], v[162:165], v[58:61]
	v_mfma_f32_16x16x32_bf16 v[42:45], v[138:141], v[170:173], v[42:45]
	v_mfma_f32_16x16x32_bf16 v[42:45], v[142:145], v[174:177], v[42:45]
	v_mfma_f32_16x16x32_bf16 v[46:49], v[134:137], v[174:177], v[46:49]
	v_mfma_f32_16x16x32_bf16 v[46:49], v[130:133], v[170:173], v[46:49]
	v_mfma_f32_16x16x32_bf16 v[30:33], v[130:133], v[178:181], v[30:33]
	v_mfma_f32_16x16x32_bf16 v[30:33], v[134:137], v[182:185], v[30:33]
	v_mfma_f32_16x16x32_bf16 v[26:29], v[142:145], v[182:185], v[26:29]
	v_mfma_f32_16x16x32_bf16 v[26:29], v[138:141], v[178:181], v[26:29]
	v_mfma_f32_16x16x32_bf16 v[10:13], v[138:141], v[186:189], v[10:13]
	v_mfma_f32_16x16x32_bf16 v[10:13], v[142:145], v[190:193], v[10:13]
	v_mfma_f32_16x16x32_bf16 v[14:17], v[134:137], v[190:193], v[14:17]
	v_mfma_f32_16x16x32_bf16 v[14:17], v[130:133], v[186:189], v[14:17]
	s_setprio 0
	s_setprio 1
	v_mfma_f32_16x16x32_bf16 v[54:57], v[146:149], v[162:165], v[54:57]
	v_mfma_f32_16x16x32_bf16 v[54:57], v[150:153], v[166:169], v[54:57]
	v_mfma_f32_16x16x32_bf16 v[50:53], v[158:161], v[166:169], v[50:53]
	v_mfma_f32_16x16x32_bf16 v[50:53], v[154:157], v[162:165], v[50:53]
	v_mfma_f32_16x16x32_bf16 v[34:37], v[154:157], v[170:173], v[34:37]
	v_mfma_f32_16x16x32_bf16 v[34:37], v[158:161], v[174:177], v[34:37]
	v_mfma_f32_16x16x32_bf16 v[38:41], v[150:153], v[174:177], v[38:41]
	v_mfma_f32_16x16x32_bf16 v[38:41], v[146:149], v[170:173], v[38:41]
	v_mfma_f32_16x16x32_bf16 v[22:25], v[146:149], v[178:181], v[22:25]
	v_mfma_f32_16x16x32_bf16 v[22:25], v[150:153], v[182:185], v[22:25]
	v_mfma_f32_16x16x32_bf16 v[18:21], v[158:161], v[182:185], v[18:21]
	v_mfma_f32_16x16x32_bf16 v[18:21], v[154:157], v[178:181], v[18:21]
	v_mfma_f32_16x16x32_bf16 v[2:5], v[154:157], v[186:189], v[2:5]
	v_mfma_f32_16x16x32_bf16 v[2:5], v[158:161], v[190:193], v[2:5]
	v_mfma_f32_16x16x32_bf16 v[6:9], v[150:153], v[190:193], v[6:9]
	v_mfma_f32_16x16x32_bf16 v[6:9], v[146:149], v[186:189], v[6:9]
	s_setprio 0
	s_barrier
	s_cmpk_gt_u32 s56, 0x55
	s_mov_b32 s56, s57
	s_cbranch_scc1 .LBB0_1449
